# GEMM4 and GEMM6 epilogues: residual loads of all rounds issued ahead (hoisted with cloned address code) instead of one exposed round trip per round
# speedup vs baseline: 1.0000x; 1.0000x over previous
; #define GAS __attribute__((address_space(1)))
;     __device__ __forceinline__ void operator()(const f32x4 (&acc)[2][2][4][2], const pg8::Unit& u, int wr, int wc, int fr, int fq) const {
;     ...
; #pragma unroll
;         for (int aim = 0; aim < 4; ++aim) { const int ai = aim >> 1, mb = (aim & 1) * 2;
;             f32x4 hx[4][2][2];
; #pragma unroll
;             for (int m = mb; m < mb + 2; ++m) { const int row = row0 + ai * 128 + m * 16;
;                 const GAS float* hp = (const GAS float*)x + ((size_t)(row / TSEG) * SEQ + (size_t)seg * TSEG + (row % TSEG)) * DM + col0;
; #pragma unroll
;                 for (int bj = 0; bj < 2; ++bj) { hx[m][bj][0] = __builtin_nontemporal_load((const GAS f32x4*)(hp + bj * 128)); hx[m][bj][1] = __builtin_nontemporal_load((const GAS f32x4*)(hp + bj * 128 + 4)); } }
.LBB0_566:
	v_lshl_add_u32 v160, s58, 8, v166
	v_ashrrev_i32_e32 v161, 31, v160
	v_lshrrev_b32_e32 v136, 20, v161
	v_add_u32_e32 v132, v160, v136
	v_ashrrev_i32_e32 v132, 12, v132
	v_lshl_or_b32 v158, s20, 8, v168
	v_mul_i32_i24_e32 v134, 0x1000, v132
	v_ashrrev_i32_e32 v159, 31, v158
	v_ashrrev_i32_e32 v133, 31, v132
	v_sub_u32_e32 v134, v160, v134
	v_ashrrev_i32_e32 v135, 31, v134
	v_lshlrev_b64 v[132:133], 27, v[132:133]
	v_lshl_add_u64 v[162:163], v[158:159], 2, s[30:31]
	v_lshlrev_b64 v[134:135], 13, v[134:135]
	v_lshl_add_u64 v[132:133], v[162:163], 0, v[132:133]
	v_lshl_add_u64 v[132:133], v[132:133], 0, v[134:135]
	global_load_dwordx4 v[184:187], v[132:133], off offset:16 nt
	global_load_dwordx4 v[188:191], v[132:133], off nt
	global_load_dwordx4 v[192:195], v[132:133], off offset:528 nt
	global_load_dwordx4 v[196:199], v[132:133], off offset:512 nt
	v_or_b32_e32 v164, 16, v160
	v_add_u32_e32 v132, v164, v136
	v_ashrrev_i32_e32 v132, 12, v132
	v_mul_i32_i24_e32 v134, 0x1000, v132
	v_ashrrev_i32_e32 v133, 31, v132
	v_sub_u32_e32 v134, v164, v134
	v_ashrrev_i32_e32 v135, 31, v134
	v_lshlrev_b64 v[132:133], 27, v[132:133]
	v_lshlrev_b64 v[134:135], 13, v[134:135]
	v_lshl_add_u64 v[132:133], v[162:163], 0, v[132:133]
	v_lshl_add_u64 v[136:137], v[132:133], 0, v[134:135]
	global_load_dwordx4 v[140:143], v[136:137], off offset:16 nt
	global_load_dwordx4 v[144:147], v[136:137], off nt
	global_load_dwordx4 v[132:135], v[136:137], off offset:528 nt
	s_nop 0
	global_load_dwordx4 v[136:139], v[136:137], off offset:512 nt
	s_nop 1
	v_ashrrev_i32_e32 v251, 31, v160
	v_lshrrev_b32_e32 v250, 20, v251
	v_or_b32_e32 v249, 32, v160
	v_add_u32_e32 v248, v249, v250
	v_ashrrev_i32_e32 v247, 12, v248
	v_mul_i32_i24_e32 v246, 0x1000, v247
	v_sub_u32_e32 v245, v249, v246
	v_ashrrev_i32_e32 v244, 31, v245
	v_mov_b32_e32 v234, v245
	v_mov_b32_e32 v235, v244
	v_lshlrev_b64 v[236:237], 13, v[234:235]
	v_ashrrev_i32_e32 v243, 31, v247
	v_mov_b32_e32 v230, v247
	v_mov_b32_e32 v231, v243
	v_lshlrev_b64 v[232:233], 27, v[230:231]
	v_lshl_add_u64 v[228:229], v[162:163], 0, v[232:233]
	v_lshl_add_u64 v[226:227], v[228:229], 0, v[236:237]
	global_load_dwordx4 v[222:225], v[226:227], off nt
	v_ashrrev_i32_e32 v251, 31, v160
	v_lshrrev_b32_e32 v250, 20, v251
	v_or_b32_e32 v249, 32, v160
	v_add_u32_e32 v248, v249, v250
	v_ashrrev_i32_e32 v247, 12, v248
	v_mul_i32_i24_e32 v246, 0x1000, v247
	v_sub_u32_e32 v245, v249, v246
	v_ashrrev_i32_e32 v244, 31, v245
	v_mov_b32_e32 v234, v245
	v_mov_b32_e32 v235, v244
	v_lshlrev_b64 v[236:237], 13, v[234:235]
	v_ashrrev_i32_e32 v243, 31, v247
	v_mov_b32_e32 v230, v247
	v_mov_b32_e32 v231, v243
	v_lshlrev_b64 v[232:233], 27, v[230:231]
	v_lshl_add_u64 v[228:229], v[162:163], 0, v[232:233]
	v_lshl_add_u64 v[226:227], v[228:229], 0, v[236:237]
	global_load_dwordx4 v[218:221], v[226:227], off offset:16 nt
	v_ashrrev_i32_e32 v251, 31, v160
	v_lshrrev_b32_e32 v250, 20, v251
	v_or_b32_e32 v249, 32, v160
	v_add_u32_e32 v248, v249, v250
	v_ashrrev_i32_e32 v247, 12, v248
	v_mul_i32_i24_e32 v246, 0x1000, v247
	v_sub_u32_e32 v245, v249, v246
	v_ashrrev_i32_e32 v244, 31, v245
	v_mov_b32_e32 v234, v245
	v_mov_b32_e32 v235, v244
	v_lshlrev_b64 v[236:237], 13, v[234:235]
	v_ashrrev_i32_e32 v243, 31, v247
	v_mov_b32_e32 v230, v247
	v_mov_b32_e32 v231, v243
	v_lshlrev_b64 v[232:233], 27, v[230:231]
	v_lshl_add_u64 v[228:229], v[162:163], 0, v[232:233]
	v_lshl_add_u64 v[226:227], v[228:229], 0, v[236:237]
	global_load_dwordx4 v[214:217], v[226:227], off offset:512 nt
	v_ashrrev_i32_e32 v251, 31, v160
	v_lshrrev_b32_e32 v250, 20, v251
	v_or_b32_e32 v249, 32, v160
	v_add_u32_e32 v248, v249, v250
	v_ashrrev_i32_e32 v247, 12, v248
	v_mul_i32_i24_e32 v246, 0x1000, v247
	v_sub_u32_e32 v245, v249, v246
	v_ashrrev_i32_e32 v244, 31, v245
	v_mov_b32_e32 v234, v245
	v_mov_b32_e32 v235, v244
	v_lshlrev_b64 v[236:237], 13, v[234:235]
	v_ashrrev_i32_e32 v243, 31, v247
	v_mov_b32_e32 v230, v247
	v_mov_b32_e32 v231, v243
	v_lshlrev_b64 v[232:233], 27, v[230:231]
	v_lshl_add_u64 v[228:229], v[162:163], 0, v[232:233]
	v_lshl_add_u64 v[226:227], v[228:229], 0, v[236:237]
	global_load_dwordx4 v[210:213], v[226:227], off offset:528 nt
	v_ashrrev_i32_e32 v251, 31, v160
	v_lshrrev_b32_e32 v250, 20, v251
	v_or_b32_e32 v249, 48, v160
	v_add_u32_e32 v248, v249, v250
	v_ashrrev_i32_e32 v247, 12, v248
	v_mul_i32_i24_e32 v246, 0x1000, v247
	v_sub_u32_e32 v245, v249, v246
	v_ashrrev_i32_e32 v244, 31, v245
	v_mov_b32_e32 v234, v245
	v_mov_b32_e32 v235, v244
	v_lshlrev_b64 v[236:237], 13, v[234:235]
	v_ashrrev_i32_e32 v243, 31, v247
	v_mov_b32_e32 v230, v247
	v_mov_b32_e32 v231, v243
	v_lshlrev_b64 v[232:233], 27, v[230:231]
	v_lshl_add_u64 v[228:229], v[162:163], 0, v[232:233]
	v_lshl_add_u64 v[226:227], v[228:229], 0, v[236:237]
	global_load_dwordx4 v[206:209], v[226:227], off offset:16 nt
	v_ashrrev_i32_e32 v251, 31, v160
	v_lshrrev_b32_e32 v250, 20, v251
	v_or_b32_e32 v249, 48, v160
	v_add_u32_e32 v248, v249, v250
	v_ashrrev_i32_e32 v247, 12, v248
	v_mul_i32_i24_e32 v246, 0x1000, v247
	v_sub_u32_e32 v245, v249, v246
	v_ashrrev_i32_e32 v244, 31, v245
	v_mov_b32_e32 v234, v245
	v_mov_b32_e32 v235, v244
	v_lshlrev_b64 v[236:237], 13, v[234:235]
	v_ashrrev_i32_e32 v243, 31, v247
	v_mov_b32_e32 v230, v247
	v_mov_b32_e32 v231, v243
	v_lshlrev_b64 v[232:233], 27, v[230:231]
	v_lshl_add_u64 v[228:229], v[162:163], 0, v[232:233]
	v_lshl_add_u64 v[226:227], v[228:229], 0, v[236:237]
	global_load_dwordx4 v[202:205], v[226:227], off nt
	v_lshlrev_b64 v[170:171], 12, v[160:161]
	v_lshl_add_u64 v[170:171], s[16:17], 0, v[170:171]
	v_lshl_add_u64 v[170:171], v[158:159], 1, v[170:171]
	s_lshl_b32 s0, s20, 2
	s_ashr_i32 s1, s0, 31
	s_waitcnt vmcnt(6)
; __device__ __forceinline__ unsigned cvt_pk_bf16(float lo, float hi) { unsigned r; asm volatile("v_cvt_pk_bf16_f32 %0, %1, %2" : "=v"(r) : "v"(lo), "v"(hi)); return r; }
; #define GAS __attribute__((address_space(1)))
;     __device__ __forceinline__ void operator()(const f32x4 (&acc)[2][2][4][2], const pg8::Unit& u, int wr, int wc, int fr, int fq) const {
;     ...
;             for (int m = mb; m < mb + 2; ++m) { const int row = row0 + ai * 128 + m * 16;
;                 float s = 0.f;
; #pragma unroll
;                 for (int bj = 0; bj < 2; ++bj) { const int col = col0 + bj * 128; const f32x4 v0 = acc[ai][bj][m][0] + hx[m][bj][0], v1 = acc[ai][bj][m][1] + hx[m][bj][1];
;                     v4u w; w.x = cvt_pk_bf16(v0[0], v0[1]); w.y = cvt_pk_bf16(v0[2], v0[3]); w.z = cvt_pk_bf16(v1[0], v1[1]); w.w = cvt_pk_bf16(v1[2], v1[3]);
;                     *(GAS v4u*)(h1b + (size_t)row * DM + col) = w;
;                     s += (v0[0] * v0[0] + v0[1] * v0[1]) + (v0[2] * v0[2] + v0[3] * v0[3]) + (v1[0] * v1[0] + v1[1] * v1[1]) + (v1[2] * v1[2] + v1[3] * v1[3]); }
;                 s += __shfl_xor(s, 16); s += __shfl_xor(s, 32);
;                 if (fq == 0) ssq[(size_t)row * 32 + u.pn * 4 + wc] = s; } }
	v_pk_add_f32 v[184:185], v[124:125], v[184:185]
	v_pk_add_f32 v[130:131], v[130:131], v[190:191]
	v_pk_add_f32 v[128:129], v[128:129], v[188:189]
	v_pk_add_f32 v[186:187], v[126:127], v[186:187]
	v_cvt_pk_bf16_f32 v124, v128, v129
	v_cvt_pk_bf16_f32 v125, v130, v131
	v_cvt_pk_bf16_f32 v126, v184, v185
	v_pk_add_f32 v[122:123], v[122:123], v[198:199]
	v_cvt_pk_bf16_f32 v127, v186, v187
	global_store_dwordx4 v[170:171], v[124:127], off
	v_ashrrev_i32_e32 v251, 31, v160
	v_lshrrev_b32_e32 v250, 20, v251
	v_or_b32_e32 v249, 48, v160
	v_add_u32_e32 v248, v249, v250
	v_ashrrev_i32_e32 v247, 12, v248
	v_mul_i32_i24_e32 v246, 0x1000, v247
	v_sub_u32_e32 v245, v249, v246
	v_ashrrev_i32_e32 v244, 31, v245
	v_mov_b32_e32 v234, v245
	v_mov_b32_e32 v235, v244
	v_lshlrev_b64 v[236:237], 13, v[234:235]
	v_ashrrev_i32_e32 v243, 31, v247
	v_mov_b32_e32 v230, v247
	v_mov_b32_e32 v231, v243
	v_lshlrev_b64 v[232:233], 27, v[230:231]
	v_lshl_add_u64 v[228:229], v[162:163], 0, v[232:233]
	v_lshl_add_u64 v[226:227], v[228:229], 0, v[236:237]
	global_load_dwordx4 v[198:201], v[226:227], off offset:528 nt
	v_ashrrev_i32_e32 v251, 31, v160
	v_lshrrev_b32_e32 v250, 20, v251
	v_or_b32_e32 v249, 48, v160
	v_add_u32_e32 v248, v249, v250
	v_ashrrev_i32_e32 v247, 12, v248
	v_mul_i32_i24_e32 v246, 0x1000, v247
	v_sub_u32_e32 v245, v249, v246
	v_ashrrev_i32_e32 v244, 31, v245
	v_mov_b32_e32 v234, v245
	v_mov_b32_e32 v235, v244
	v_lshlrev_b64 v[236:237], 13, v[234:235]
	v_ashrrev_i32_e32 v243, 31, v247
	v_mov_b32_e32 v230, v247
	v_mov_b32_e32 v231, v243
	v_lshlrev_b64 v[232:233], 27, v[230:231]
	v_lshl_add_u64 v[228:229], v[162:163], 0, v[232:233]
	v_lshl_add_u64 v[226:227], v[228:229], 0, v[236:237]
	global_load_dwordx4 v[188:191], v[226:227], off offset:512 nt
	v_pk_add_f32 v[120:121], v[120:121], v[196:197]
	s_nop 0
	v_mul_f32_e32 v124, v129, v129
	v_mul_f32_e32 v125, v131, v131
	v_fmac_f32_e32 v124, v128, v128
	v_fmac_f32_e32 v125, v130, v130
	v_add_f32_e32 v124, v124, v125
	v_mul_f32_e32 v125, v185, v185
	v_fmac_f32_e32 v125, v184, v184
	v_add_f32_e32 v124, v124, v125
	v_mul_f32_e32 v125, v187, v187
	v_fmac_f32_e32 v125, v186, v186
	v_pk_add_f32 v[126:127], v[116:117], v[192:193]
	v_cvt_pk_bf16_f32 v116, v120, v121
	v_cvt_pk_bf16_f32 v117, v122, v123
	v_add_f32_e32 v128, v125, v124
	v_pk_add_f32 v[124:125], v[118:119], v[194:195]
	v_cvt_pk_bf16_f32 v118, v126, v127
	s_nop 0
	v_cvt_pk_bf16_f32 v119, v124, v125
	global_store_dwordx4 v[170:171], v[116:119], off offset:256
	v_add_u32_e32 v251, 0x80, v160
	v_ashrrev_i32_e32 v250, 31, v251
	v_lshrrev_b32_e32 v249, 20, v250
	v_add_u32_e32 v248, v251, v249
	v_ashrrev_i32_e32 v247, 12, v248
	v_mul_i32_i24_e32 v246, 0x1000, v247
	v_sub_u32_e32 v245, v251, v246
	v_ashrrev_i32_e32 v244, 31, v245
	v_mov_b32_e32 v234, v245
	v_mov_b32_e32 v235, v244
	v_lshlrev_b64 v[236:237], 13, v[234:235]
	v_ashrrev_i32_e32 v243, 31, v247
	v_mov_b32_e32 v230, v247
	v_mov_b32_e32 v231, v243
	v_lshlrev_b64 v[232:233], 27, v[230:231]
	v_lshl_add_u64 v[228:229], v[162:163], 0, v[232:233]
	v_lshl_add_u64 v[226:227], v[228:229], 0, v[236:237]
	global_load_dwordx4 v[194:197], v[226:227], off nt
	v_add_u32_e32 v251, 0x80, v160
	v_ashrrev_i32_e32 v250, 31, v251
	v_lshrrev_b32_e32 v249, 20, v250
	v_add_u32_e32 v248, v251, v249
	v_ashrrev_i32_e32 v247, 12, v248
	v_mul_i32_i24_e32 v246, 0x1000, v247
	v_sub_u32_e32 v245, v251, v246
	v_ashrrev_i32_e32 v244, 31, v245
	v_mov_b32_e32 v234, v245
	v_mov_b32_e32 v235, v244
	v_lshlrev_b64 v[236:237], 13, v[234:235]
	v_ashrrev_i32_e32 v243, 31, v247
	v_mov_b32_e32 v230, v247
	v_mov_b32_e32 v231, v243
	v_lshlrev_b64 v[232:233], 27, v[230:231]
	v_lshl_add_u64 v[228:229], v[162:163], 0, v[232:233]
	v_lshl_add_u64 v[226:227], v[228:229], 0, v[236:237]
	global_load_dwordx4 v[184:187], v[226:227], off offset:16 nt
	s_nop 1
	v_mul_f32_e32 v116, v121, v121
	v_mul_f32_e32 v117, v123, v123
	v_fmac_f32_e32 v116, v120, v120
	v_fmac_f32_e32 v117, v122, v122
	v_add_f32_e32 v116, v116, v117
	v_mul_f32_e32 v117, v127, v127
	v_fmac_f32_e32 v117, v126, v126
	v_add_f32_e32 v116, v116, v117
	v_mul_f32_e32 v117, v125, v125
	v_fmac_f32_e32 v117, v124, v124
	v_and_b32_e32 v118, 64, v173
	v_add_f32_e32 v116, v117, v116
	v_xor_b32_e32 v117, 16, v173
	v_add_u32_e32 v118, 64, v118
	v_cmp_lt_i32_e32 vcc, v117, v118
	v_add_f32_e32 v116, v128, v116
	s_nop 0
	v_cndmask_b32_e32 v117, v173, v117, vcc
	v_lshlrev_b32_e32 v120, 2, v117
	ds_bpermute_b32 v117, v120, v116
	s_waitcnt lgkmcnt(0)
	v_add_f32_e32 v116, v116, v117
	v_xor_b32_e32 v117, 32, v173
	v_cmp_lt_i32_e32 vcc, v117, v118
	s_nop 1
	v_cndmask_b32_e32 v117, v173, v117, vcc
	v_lshlrev_b32_e32 v121, 2, v117
	ds_bpermute_b32 v117, v121, v116
	s_and_saveexec_b64 s[18:19], s[40:41]
	s_cbranch_execz .LBB0_568
	v_lshlrev_b64 v[118:119], 7, v[160:161]
	v_lshl_add_u64 v[118:119], s[28:29], 0, v[118:119]
	v_lshl_add_u64 v[118:119], s[0:1], 2, v[118:119]
	s_lshl_b32 s20, s53, 2
	v_lshl_add_u64 v[118:119], v[118:119], 0, s[20:21]
	s_waitcnt lgkmcnt(0)
	v_add_f32_e32 v116, v116, v117
	global_store_dword v[118:119], v116, off
; __device__ __forceinline__ unsigned cvt_pk_bf16(float lo, float hi) { unsigned r; asm volatile("v_cvt_pk_bf16_f32 %0, %1, %2" : "=v"(r) : "v"(lo), "v"(hi)); return r; }
; #define GAS __attribute__((address_space(1)))
;     __device__ __forceinline__ void operator()(const f32x4 (&acc)[2][2][4][2], const pg8::Unit& u, int wr, int wc, int fr, int fq) const {
;     ...
;             for (int m = mb; m < mb + 2; ++m) { const int row = row0 + ai * 128 + m * 16;
;                 float s = 0.f;
; #pragma unroll
;                 for (int bj = 0; bj < 2; ++bj) { const int col = col0 + bj * 128; const f32x4 v0 = acc[ai][bj][m][0] + hx[m][bj][0], v1 = acc[ai][bj][m][1] + hx[m][bj][1];
;                     v4u w; w.x = cvt_pk_bf16(v0[0], v0[1]); w.y = cvt_pk_bf16(v0[2], v0[3]); w.z = cvt_pk_bf16(v1[0], v1[1]); w.w = cvt_pk_bf16(v1[2], v1[3]);
;                     *(GAS v4u*)(h1b + (size_t)row * DM + col) = w;
;                     s += (v0[0] * v0[0] + v0[1] * v0[1]) + (v0[2] * v0[2] + v0[3] * v0[3]) + (v1[0] * v1[0] + v1[1] * v1[1]) + (v1[2] * v1[2] + v1[3] * v1[3]); }
;                 s += __shfl_xor(s, 16); s += __shfl_xor(s, 32);
;                 if (fq == 0) ssq[(size_t)row * 32 + u.pn * 4 + wc] = s; } }
.LBB0_568:
	s_or_b64 exec, exec, s[18:19]
	v_pk_add_f32 v[112:113], v[112:113], v[144:145]
	v_pk_add_f32 v[114:115], v[114:115], v[146:147]
	v_pk_add_f32 v[122:123], v[108:109], v[140:141]
	v_cvt_pk_bf16_f32 v108, v112, v113
	v_mul_f32_e32 v113, v113, v113
	v_fmac_f32_e32 v113, v112, v112
	v_mul_f32_e32 v112, v115, v115
	v_fmac_f32_e32 v112, v114, v114
	v_add_f32_e32 v112, v113, v112
	v_mul_f32_e32 v113, v123, v123
	v_pk_add_f32 v[106:107], v[106:107], v[138:139]
	v_pk_add_f32 v[104:105], v[104:105], v[136:137]
	v_pk_add_f32 v[118:119], v[110:111], v[142:143]
	v_cvt_pk_bf16_f32 v109, v114, v115
	v_fmac_f32_e32 v113, v122, v122
	v_pk_add_f32 v[114:115], v[100:101], v[132:133]
	v_mul_f32_e32 v100, v105, v105
	v_mul_f32_e32 v101, v107, v107
	v_add_f32_e32 v112, v112, v113
	v_mul_f32_e32 v113, v119, v119
	v_fmac_f32_e32 v100, v104, v104
	v_fmac_f32_e32 v101, v106, v106
	v_fmac_f32_e32 v113, v118, v118
	v_add_f32_e32 v100, v100, v101
	v_mul_f32_e32 v101, v115, v115
	v_cvt_pk_bf16_f32 v110, v122, v123
	v_cvt_pk_bf16_f32 v111, v118, v119
	v_add_f32_e32 v118, v113, v112
	v_pk_add_f32 v[112:113], v[102:103], v[134:135]
	v_fmac_f32_e32 v101, v114, v114
	v_add_f32_e32 v100, v100, v101
	v_mul_f32_e32 v101, v113, v113
	v_fmac_f32_e32 v101, v112, v112
	v_add_f32_e32 v100, v101, v100
	v_add_f32_e32 v103, v118, v100
	ds_bpermute_b32 v118, v120, v103
	v_ashrrev_i32_e32 v165, 31, v164
	s_waitcnt lgkmcnt(1)
	v_lshlrev_b64 v[116:117], 12, v[164:165]
	v_lshl_add_u64 v[100:101], s[16:17], 0, v[116:117]
	v_lshl_add_u64 v[116:117], v[158:159], 1, v[100:101]
	s_waitcnt lgkmcnt(0)
	v_add_f32_e32 v100, v103, v118
	ds_bpermute_b32 v101, v121, v100
	global_store_dwordx4 v[116:117], v[108:111], off
	v_add_u32_e32 v251, 0x80, v160
	v_ashrrev_i32_e32 v250, 31, v251
	v_lshrrev_b32_e32 v249, 20, v250
	v_add_u32_e32 v248, v251, v249
	v_ashrrev_i32_e32 v247, 12, v248
	v_mul_i32_i24_e32 v246, 0x1000, v247
	v_sub_u32_e32 v245, v251, v246
	v_ashrrev_i32_e32 v244, 31, v245
	v_mov_b32_e32 v234, v245
	v_mov_b32_e32 v235, v244
	v_lshlrev_b64 v[236:237], 13, v[234:235]
	v_ashrrev_i32_e32 v243, 31, v247
	v_mov_b32_e32 v230, v247
	v_mov_b32_e32 v231, v243
	v_lshlrev_b64 v[232:233], 27, v[230:231]
	v_lshl_add_u64 v[228:229], v[162:163], 0, v[232:233]
	v_lshl_add_u64 v[226:227], v[228:229], 0, v[236:237]
	global_load_dwordx4 v[144:147], v[226:227], off offset:512 nt
	v_add_u32_e32 v251, 0x80, v160
	v_ashrrev_i32_e32 v250, 31, v251
	v_lshrrev_b32_e32 v249, 20, v250
	v_add_u32_e32 v248, v251, v249
	v_ashrrev_i32_e32 v247, 12, v248
	v_mul_i32_i24_e32 v246, 0x1000, v247
	v_sub_u32_e32 v245, v251, v246
	v_ashrrev_i32_e32 v244, 31, v245
	v_mov_b32_e32 v234, v245
	v_mov_b32_e32 v235, v244
	v_lshlrev_b64 v[236:237], 13, v[234:235]
	v_ashrrev_i32_e32 v243, 31, v247
	v_mov_b32_e32 v230, v247
	v_mov_b32_e32 v231, v243
	v_lshlrev_b64 v[232:233], 27, v[230:231]
	v_lshl_add_u64 v[228:229], v[162:163], 0, v[232:233]
	v_lshl_add_u64 v[226:227], v[228:229], 0, v[236:237]
	global_load_dwordx4 v[140:143], v[226:227], off offset:528 nt
	v_add_u32_e32 v251, 0x90, v160
	v_ashrrev_i32_e32 v250, 31, v251
	v_lshrrev_b32_e32 v249, 20, v250
	v_add_u32_e32 v248, v251, v249
	v_ashrrev_i32_e32 v247, 12, v248
	v_mul_i32_i24_e32 v246, 0x1000, v247
	v_sub_u32_e32 v245, v251, v246
	v_ashrrev_i32_e32 v244, 31, v245
	v_mov_b32_e32 v234, v245
	v_mov_b32_e32 v235, v244
	v_lshlrev_b64 v[236:237], 13, v[234:235]
	v_ashrrev_i32_e32 v243, 31, v247
	v_mov_b32_e32 v230, v247
	v_mov_b32_e32 v231, v243
	v_lshlrev_b64 v[232:233], 27, v[230:231]
	v_lshl_add_u64 v[228:229], v[162:163], 0, v[232:233]
	v_lshl_add_u64 v[226:227], v[228:229], 0, v[236:237]
	global_load_dwordx4 v[134:137], v[226:227], off offset:16 nt
	v_add_u32_e32 v251, 0x90, v160
	v_ashrrev_i32_e32 v250, 31, v251
	v_lshrrev_b32_e32 v249, 20, v250
	v_add_u32_e32 v248, v251, v249
	v_ashrrev_i32_e32 v247, 12, v248
	v_mul_i32_i24_e32 v246, 0x1000, v247
	v_sub_u32_e32 v245, v251, v246
	v_ashrrev_i32_e32 v244, 31, v245
	v_mov_b32_e32 v234, v245
	v_mov_b32_e32 v235, v244
	v_lshlrev_b64 v[236:237], 13, v[234:235]
	v_ashrrev_i32_e32 v243, 31, v247
	v_mov_b32_e32 v230, v247
	v_mov_b32_e32 v231, v243
	v_lshlrev_b64 v[232:233], 27, v[230:231]
	v_lshl_add_u64 v[228:229], v[162:163], 0, v[232:233]
	v_lshl_add_u64 v[226:227], v[228:229], 0, v[236:237]
	global_load_dwordx4 v[130:133], v[226:227], off nt
	v_add_u32_e32 v251, 0x90, v160
	v_ashrrev_i32_e32 v250, 31, v251
	v_lshrrev_b32_e32 v249, 20, v250
	v_add_u32_e32 v248, v251, v249
	v_ashrrev_i32_e32 v247, 12, v248
	v_mul_i32_i24_e32 v246, 0x1000, v247
	v_sub_u32_e32 v245, v251, v246
	v_ashrrev_i32_e32 v244, 31, v245
	v_mov_b32_e32 v234, v245
	v_mov_b32_e32 v235, v244
	v_lshlrev_b64 v[236:237], 13, v[234:235]
	v_ashrrev_i32_e32 v243, 31, v247
	v_mov_b32_e32 v230, v247
	v_mov_b32_e32 v231, v243
	v_lshlrev_b64 v[232:233], 27, v[230:231]
	v_lshl_add_u64 v[228:229], v[162:163], 0, v[232:233]
	v_lshl_add_u64 v[226:227], v[228:229], 0, v[236:237]
	global_load_dwordx4 v[108:111], v[226:227], off offset:528 nt
	v_cvt_pk_bf16_f32 v102, v104, v105
	v_cvt_pk_bf16_f32 v103, v106, v107
	v_cvt_pk_bf16_f32 v104, v114, v115
	v_cvt_pk_bf16_f32 v105, v112, v113
	global_store_dwordx4 v[116:117], v[102:105], off offset:256
	v_add_u32_e32 v251, 0x90, v160
	v_ashrrev_i32_e32 v250, 31, v251
	v_lshrrev_b32_e32 v249, 20, v250
	v_add_u32_e32 v248, v251, v249
	v_ashrrev_i32_e32 v247, 12, v248
	v_mul_i32_i24_e32 v246, 0x1000, v247
	v_sub_u32_e32 v245, v251, v246
	v_ashrrev_i32_e32 v244, 31, v245
	v_mov_b32_e32 v234, v245
	v_mov_b32_e32 v235, v244
	v_lshlrev_b64 v[236:237], 13, v[234:235]
	v_ashrrev_i32_e32 v243, 31, v247
	v_mov_b32_e32 v230, v247
	v_mov_b32_e32 v231, v243
	v_lshlrev_b64 v[232:233], 27, v[230:231]
	v_lshl_add_u64 v[228:229], v[162:163], 0, v[232:233]
	v_lshl_add_u64 v[226:227], v[228:229], 0, v[236:237]
	global_load_dwordx4 v[112:115], v[226:227], off offset:512 nt
	s_and_saveexec_b64 s[18:19], s[40:41]
	s_cbranch_execz .LBB0_570
	v_lshlrev_b64 v[102:103], 7, v[164:165]
	v_lshl_add_u64 v[102:103], s[28:29], 0, v[102:103]
	v_lshl_add_u64 v[102:103], s[0:1], 2, v[102:103]
	s_lshl_b32 s20, s53, 2
	v_lshl_add_u64 v[102:103], v[102:103], 0, s[20:21]
	s_waitcnt lgkmcnt(0)
	v_add_f32_e32 v100, v100, v101
	global_store_dword v[102:103], v100, off
; __device__ __forceinline__ unsigned cvt_pk_bf16(float lo, float hi) { unsigned r; asm volatile("v_cvt_pk_bf16_f32 %0, %1, %2" : "=v"(r) : "v"(lo), "v"(hi)); return r; }
; #define GAS __attribute__((address_space(1)))
;     __device__ __forceinline__ void operator()(const f32x4 (&acc)[2][2][4][2], const pg8::Unit& u, int wr, int wc, int fr, int fq) const {
;     ...
; #pragma unroll
;         for (int aim = 0; aim < 4; ++aim) { const int ai = aim >> 1, mb = (aim & 1) * 2;
;             f32x4 hx[4][2][2];
; #pragma unroll
;             for (int m = mb; m < mb + 2; ++m) { const int row = row0 + ai * 128 + m * 16;
;                 const GAS float* hp = (const GAS float*)x + ((size_t)(row / TSEG) * SEQ + (size_t)seg * TSEG + (row % TSEG)) * DM + col0;
; #pragma unroll
;                 for (int bj = 0; bj < 2; ++bj) { hx[m][bj][0] = __builtin_nontemporal_load((const GAS f32x4*)(hp + bj * 128)); hx[m][bj][1] = __builtin_nontemporal_load((const GAS f32x4*)(hp + bj * 128 + 4)); } }
; #pragma unroll
;             for (int m = mb; m < mb + 2; ++m) { const int row = row0 + ai * 128 + m * 16;
;                 float s = 0.f;
; #pragma unroll
;                 for (int bj = 0; bj < 2; ++bj) { const int col = col0 + bj * 128; const f32x4 v0 = acc[ai][bj][m][0] + hx[m][bj][0], v1 = acc[ai][bj][m][1] + hx[m][bj][1];
;                     v4u w; w.x = cvt_pk_bf16(v0[0], v0[1]); w.y = cvt_pk_bf16(v0[2], v0[3]); w.z = cvt_pk_bf16(v1[0], v1[1]); w.w = cvt_pk_bf16(v1[2], v1[3]);
;                     *(GAS v4u*)(h1b + (size_t)row * DM + col) = w;
;                     s += (v0[0] * v0[0] + v0[1] * v0[1]) + (v0[2] * v0[2] + v0[3] * v0[3]) + (v1[0] * v1[0] + v1[1] * v1[1]) + (v1[2] * v1[2] + v1[3] * v1[3]); }
;                 s += __shfl_xor(s, 16); s += __shfl_xor(s, 32);
;                 if (fq == 0) ssq[(size_t)row * 32 + u.pn * 4 + wc] = s; } }
.LBB0_570:
	s_or_b64 exec, exec, s[18:19]
	v_ashrrev_i32_e32 v100, 31, v160
	v_or_b32_e32 v118, 32, v160
	v_lshrrev_b32_e32 v104, 20, v100
	v_add_u32_e32 v100, v118, v104
	v_ashrrev_i32_e32 v100, 12, v100
	v_mul_i32_i24_e32 v102, 0x1000, v100
	s_waitcnt lgkmcnt(0)
	v_ashrrev_i32_e32 v101, 31, v100
	v_sub_u32_e32 v102, v118, v102
	v_ashrrev_i32_e32 v103, 31, v102
	v_lshlrev_b64 v[100:101], 27, v[100:101]
	v_lshlrev_b64 v[102:103], 13, v[102:103]
	v_lshl_add_u64 v[100:101], v[162:163], 0, v[100:101]
	v_lshl_add_u64 v[100:101], v[100:101], 0, v[102:103]
	s_nop 0
	s_nop 0
	s_nop 0
	s_nop 0
	v_or_b32_e32 v116, 48, v160
	v_add_u32_e32 v100, v116, v104
	v_ashrrev_i32_e32 v100, 12, v100
	v_mul_i32_i24_e32 v102, 0x1000, v100
	v_ashrrev_i32_e32 v101, 31, v100
	v_sub_u32_e32 v102, v116, v102
	v_lshlrev_b64 v[100:101], 27, v[100:101]
	v_ashrrev_i32_e32 v103, 31, v102
	v_lshl_add_u64 v[100:101], v[162:163], 0, v[100:101]
	v_lshlrev_b64 v[102:103], 13, v[102:103]
	v_lshl_add_u64 v[104:105], v[100:101], 0, v[102:103]
	s_nop 0
	s_nop 0
	s_nop 0
	s_nop 0
	s_nop 0
	v_ashrrev_i32_e32 v119, 31, v118
	v_lshlrev_b64 v[138:139], 12, v[118:119]
	s_waitcnt vmcnt(19)
	v_pk_add_f32 v[98:99], v[98:99], v[224:225]
	v_pk_add_f32 v[96:97], v[96:97], v[222:223]
	s_waitcnt vmcnt(17)
	v_pk_add_f32 v[90:91], v[90:91], v[216:217]
	v_pk_add_f32 v[88:89], v[88:89], v[214:215]
	v_pk_add_f32 v[94:95], v[94:95], v[220:221]
	v_pk_add_f32 v[92:93], v[92:93], v[218:219]
	s_waitcnt vmcnt(16)
	v_pk_add_f32 v[124:125], v[84:85], v[210:211]
	v_cvt_pk_bf16_f32 v84, v96, v97
	v_cvt_pk_bf16_f32 v85, v98, v99
	v_mul_f32_e32 v97, v97, v97
	v_mul_f32_e32 v99, v99, v99
	v_mul_f32_e32 v117, v89, v89
	v_mul_f32_e32 v126, v91, v91
	v_pk_add_f32 v[122:123], v[86:87], v[212:213]
	v_cvt_pk_bf16_f32 v86, v92, v93
	v_cvt_pk_bf16_f32 v87, v94, v95
	v_mul_f32_e32 v93, v93, v93
	v_mul_f32_e32 v95, v95, v95
	v_mul_f32_e32 v127, v125, v125
	v_fmac_f32_e32 v97, v96, v96
	v_fmac_f32_e32 v99, v98, v98
	v_fmac_f32_e32 v117, v88, v88
	v_fmac_f32_e32 v126, v90, v90
	v_mul_f32_e32 v128, v123, v123
	v_fmac_f32_e32 v93, v92, v92
	v_fmac_f32_e32 v95, v94, v94
	v_fmac_f32_e32 v127, v124, v124
	v_add_f32_e32 v92, v97, v99
	v_add_f32_e32 v94, v117, v126
	v_fmac_f32_e32 v128, v122, v122
	v_add_f32_e32 v92, v92, v93
	v_add_f32_e32 v93, v94, v127
	v_add_f32_e32 v92, v95, v92
	v_add_f32_e32 v93, v128, v93
	v_add_f32_e32 v94, v92, v93
	ds_bpermute_b32 v95, v120, v94
	v_lshl_add_u64 v[92:93], s[16:17], 0, v[138:139]
	v_lshl_add_u64 v[92:93], v[158:159], 1, v[92:93]
	global_store_dwordx4 v[92:93], v[84:87], off
	v_add_u32_e32 v251, 0xa0, v160
	v_ashrrev_i32_e32 v250, 31, v251
	v_lshrrev_b32_e32 v249, 20, v250
	v_add_u32_e32 v248, v251, v249
	v_ashrrev_i32_e32 v247, 12, v248
	v_mul_i32_i24_e32 v246, 0x1000, v247
	v_sub_u32_e32 v245, v251, v246
	v_ashrrev_i32_e32 v244, 31, v245
	v_mov_b32_e32 v234, v245
	v_mov_b32_e32 v235, v244
	v_lshlrev_b64 v[236:237], 13, v[234:235]
	v_ashrrev_i32_e32 v243, 31, v247
	v_mov_b32_e32 v230, v247
	v_mov_b32_e32 v231, v243
	v_lshlrev_b64 v[232:233], 27, v[230:231]
	v_lshl_add_u64 v[228:229], v[162:163], 0, v[232:233]
	v_lshl_add_u64 v[226:227], v[228:229], 0, v[236:237]
	global_load_dwordx4 v[222:225], v[226:227], off nt
	v_add_u32_e32 v251, 0xa0, v160
	v_ashrrev_i32_e32 v250, 31, v251
	v_lshrrev_b32_e32 v249, 20, v250
	v_add_u32_e32 v248, v251, v249
	v_ashrrev_i32_e32 v247, 12, v248
	v_mul_i32_i24_e32 v246, 0x1000, v247
	v_sub_u32_e32 v245, v251, v246
	v_ashrrev_i32_e32 v244, 31, v245
	v_mov_b32_e32 v234, v245
	v_mov_b32_e32 v235, v244
	v_lshlrev_b64 v[236:237], 13, v[234:235]
	v_ashrrev_i32_e32 v243, 31, v247
	v_mov_b32_e32 v230, v247
	v_mov_b32_e32 v231, v243
	v_lshlrev_b64 v[232:233], 27, v[230:231]
	v_lshl_add_u64 v[228:229], v[162:163], 0, v[232:233]
	v_lshl_add_u64 v[226:227], v[228:229], 0, v[236:237]
	global_load_dwordx4 v[218:221], v[226:227], off offset:16 nt
	v_add_u32_e32 v251, 0xa0, v160
	v_ashrrev_i32_e32 v250, 31, v251
	v_lshrrev_b32_e32 v249, 20, v250
	v_add_u32_e32 v248, v251, v249
	v_ashrrev_i32_e32 v247, 12, v248
	v_mul_i32_i24_e32 v246, 0x1000, v247
	v_sub_u32_e32 v245, v251, v246
	v_ashrrev_i32_e32 v244, 31, v245
	v_mov_b32_e32 v234, v245
	v_mov_b32_e32 v235, v244
	v_lshlrev_b64 v[236:237], 13, v[234:235]
	v_ashrrev_i32_e32 v243, 31, v247
	v_mov_b32_e32 v230, v247
	v_mov_b32_e32 v231, v243
	v_lshlrev_b64 v[232:233], 27, v[230:231]
	v_lshl_add_u64 v[228:229], v[162:163], 0, v[232:233]
	v_lshl_add_u64 v[226:227], v[228:229], 0, v[236:237]
	global_load_dwordx4 v[214:217], v[226:227], off offset:512 nt
	v_add_u32_e32 v251, 0xa0, v160
	v_ashrrev_i32_e32 v250, 31, v251
	v_lshrrev_b32_e32 v249, 20, v250
	v_add_u32_e32 v248, v251, v249
	v_ashrrev_i32_e32 v247, 12, v248
	v_mul_i32_i24_e32 v246, 0x1000, v247
	v_sub_u32_e32 v245, v251, v246
	v_ashrrev_i32_e32 v244, 31, v245
	v_mov_b32_e32 v234, v245
	v_mov_b32_e32 v235, v244
	v_lshlrev_b64 v[236:237], 13, v[234:235]
	v_ashrrev_i32_e32 v243, 31, v247
	v_mov_b32_e32 v230, v247
	v_mov_b32_e32 v231, v243
	v_lshlrev_b64 v[232:233], 27, v[230:231]
	v_lshl_add_u64 v[228:229], v[162:163], 0, v[232:233]
	v_lshl_add_u64 v[226:227], v[228:229], 0, v[236:237]
	global_load_dwordx4 v[210:213], v[226:227], off offset:528 nt
	v_add_u32_e32 v251, 0xb0, v160
	v_ashrrev_i32_e32 v250, 31, v251
	v_lshrrev_b32_e32 v249, 20, v250
	v_add_u32_e32 v248, v251, v249
	v_ashrrev_i32_e32 v247, 12, v248
	v_mul_i32_i24_e32 v246, 0x1000, v247
	v_sub_u32_e32 v245, v251, v246
	v_ashrrev_i32_e32 v244, 31, v245
	v_mov_b32_e32 v234, v245
	v_mov_b32_e32 v235, v244
	v_lshlrev_b64 v[236:237], 13, v[234:235]
	v_ashrrev_i32_e32 v243, 31, v247
	v_mov_b32_e32 v230, v247
; __device__ __forceinline__ unsigned cvt_pk_bf16(float lo, float hi) { unsigned r; asm volatile("v_cvt_pk_bf16_f32 %0, %1, %2" : "=v"(r) : "v"(lo), "v"(hi)); return r; }
; #define GAS __attribute__((address_space(1)))
;     __device__ __forceinline__ void operator()(const f32x4 (&acc)[2][2][4][2], const pg8::Unit& u, int wr, int wc, int fr, int fq) const {
;     ...
;             for (int m = mb; m < mb + 2; ++m) { const int row = row0 + ai * 128 + m * 16;
;                 float s = 0.f;
; #pragma unroll
;                 for (int bj = 0; bj < 2; ++bj) { const int col = col0 + bj * 128; const f32x4 v0 = acc[ai][bj][m][0] + hx[m][bj][0], v1 = acc[ai][bj][m][1] + hx[m][bj][1];
;                     v4u w; w.x = cvt_pk_bf16(v0[0], v0[1]); w.y = cvt_pk_bf16(v0[2], v0[3]); w.z = cvt_pk_bf16(v1[0], v1[1]); w.w = cvt_pk_bf16(v1[2], v1[3]);
;                     *(GAS v4u*)(h1b + (size_t)row * DM + col) = w;
;                     s += (v0[0] * v0[0] + v0[1] * v0[1]) + (v0[2] * v0[2] + v0[3] * v0[3]) + (v1[0] * v1[0] + v1[1] * v1[1]) + (v1[2] * v1[2] + v1[3] * v1[3]); }
;                 s += __shfl_xor(s, 16); s += __shfl_xor(s, 32);
;                 if (fq == 0) ssq[(size_t)row * 32 + u.pn * 4 + wc] = s; } }
	v_mov_b32_e32 v231, v243
	v_lshlrev_b64 v[232:233], 27, v[230:231]
	v_lshl_add_u64 v[228:229], v[162:163], 0, v[232:233]
	v_lshl_add_u64 v[226:227], v[228:229], 0, v[236:237]
	global_load_dwordx4 v[126:129], v[226:227], off offset:16 nt
	v_add_u32_e32 v251, 0xb0, v160
	v_ashrrev_i32_e32 v250, 31, v251
	v_lshrrev_b32_e32 v249, 20, v250
	v_add_u32_e32 v248, v251, v249
	v_ashrrev_i32_e32 v247, 12, v248
	v_mul_i32_i24_e32 v246, 0x1000, v247
	v_sub_u32_e32 v245, v251, v246
	v_ashrrev_i32_e32 v244, 31, v245
	v_mov_b32_e32 v234, v245
	v_mov_b32_e32 v235, v244
	v_lshlrev_b64 v[236:237], 13, v[234:235]
	v_ashrrev_i32_e32 v243, 31, v247
	v_mov_b32_e32 v230, v247
	v_mov_b32_e32 v231, v243
	v_lshlrev_b64 v[232:233], 27, v[230:231]
	v_lshl_add_u64 v[228:229], v[162:163], 0, v[232:233]
	v_lshl_add_u64 v[226:227], v[228:229], 0, v[236:237]
	global_load_dwordx4 v[100:103], v[226:227], off nt
	v_add_u32_e32 v251, 0xb0, v160
	v_ashrrev_i32_e32 v250, 31, v251
	v_lshrrev_b32_e32 v249, 20, v250
	v_add_u32_e32 v248, v251, v249
	v_ashrrev_i32_e32 v247, 12, v248
	v_mul_i32_i24_e32 v246, 0x1000, v247
	v_sub_u32_e32 v245, v251, v246
	v_ashrrev_i32_e32 v244, 31, v245
	v_mov_b32_e32 v234, v245
	v_mov_b32_e32 v235, v244
	v_lshlrev_b64 v[236:237], 13, v[234:235]
	v_ashrrev_i32_e32 v243, 31, v247
	v_mov_b32_e32 v230, v247
	v_mov_b32_e32 v231, v243
	v_lshlrev_b64 v[232:233], 27, v[230:231]
	v_lshl_add_u64 v[228:229], v[162:163], 0, v[232:233]
	v_lshl_add_u64 v[226:227], v[228:229], 0, v[236:237]
	global_load_dwordx4 v[96:99], v[226:227], off offset:528 nt
	s_waitcnt lgkmcnt(0)
	s_nop 0
	v_add_f32_e32 v84, v94, v95
	ds_bpermute_b32 v85, v121, v84
	v_cvt_pk_bf16_f32 v86, v88, v89
	v_cvt_pk_bf16_f32 v87, v90, v91
	v_cvt_pk_bf16_f32 v88, v124, v125
	v_cvt_pk_bf16_f32 v89, v122, v123
	global_store_dwordx4 v[92:93], v[86:89], off offset:256
	v_add_u32_e32 v251, 0xb0, v160
	v_ashrrev_i32_e32 v250, 31, v251
	v_lshrrev_b32_e32 v249, 20, v250
	v_add_u32_e32 v248, v251, v249
	v_ashrrev_i32_e32 v247, 12, v248
	v_mul_i32_i24_e32 v246, 0x1000, v247
	v_sub_u32_e32 v245, v251, v246
	v_ashrrev_i32_e32 v244, 31, v245
	v_mov_b32_e32 v234, v245
	v_mov_b32_e32 v235, v244
	v_lshlrev_b64 v[236:237], 13, v[234:235]
	v_ashrrev_i32_e32 v243, 31, v247
	v_mov_b32_e32 v230, v247
	v_mov_b32_e32 v231, v243
	v_lshlrev_b64 v[232:233], 27, v[230:231]
	v_lshl_add_u64 v[228:229], v[162:163], 0, v[232:233]
	v_lshl_add_u64 v[226:227], v[228:229], 0, v[236:237]
	global_load_dwordx4 v[122:125], v[226:227], off offset:512 nt
	s_and_saveexec_b64 s[18:19], s[40:41]
	s_cbranch_execz .LBB0_572
	v_lshlrev_b64 v[86:87], 7, v[118:119]
	v_lshl_add_u64 v[86:87], s[28:29], 0, v[86:87]
	v_lshl_add_u64 v[86:87], s[0:1], 2, v[86:87]
	s_lshl_b32 s20, s53, 2
	v_lshl_add_u64 v[86:87], v[86:87], 0, s[20:21]
	s_waitcnt lgkmcnt(0)
	v_add_f32_e32 v84, v84, v85
	global_store_dword v[86:87], v84, off
.LBB0_572:
	s_or_b64 exec, exec, s[18:19]
	s_waitcnt vmcnt(22)
	v_pk_add_f32 v[80:81], v[80:81], v[202:203]
	v_pk_add_f32 v[82:83], v[82:83], v[204:205]
	v_pk_add_f32 v[88:89], v[76:77], v[206:207]
	v_cvt_pk_bf16_f32 v76, v80, v81
	v_mul_f32_e32 v81, v81, v81
	v_fmac_f32_e32 v81, v80, v80
	v_mul_f32_e32 v80, v83, v83
	v_fmac_f32_e32 v80, v82, v82
	v_add_f32_e32 v80, v81, v80
	v_mul_f32_e32 v81, v89, v89
	s_waitcnt vmcnt(21)
	v_pk_add_f32 v[74:75], v[74:75], v[190:191]
	v_pk_add_f32 v[72:73], v[72:73], v[188:189]
	v_pk_add_f32 v[86:87], v[78:79], v[208:209]
	v_cvt_pk_bf16_f32 v77, v82, v83
	v_fmac_f32_e32 v81, v88, v88
	v_pk_add_f32 v[82:83], v[68:69], v[198:199]
	v_mul_f32_e32 v68, v73, v73
	v_mul_f32_e32 v69, v75, v75
	v_add_f32_e32 v80, v80, v81
	v_mul_f32_e32 v81, v87, v87
	v_fmac_f32_e32 v68, v72, v72
	v_fmac_f32_e32 v69, v74, v74
	v_fmac_f32_e32 v81, v86, v86
	v_add_f32_e32 v68, v68, v69
	v_mul_f32_e32 v69, v83, v83
	v_cvt_pk_bf16_f32 v78, v88, v89
	v_cvt_pk_bf16_f32 v79, v86, v87
	v_add_f32_e32 v86, v81, v80
	v_pk_add_f32 v[80:81], v[70:71], v[200:201]
	v_fmac_f32_e32 v69, v82, v82
	v_add_f32_e32 v68, v68, v69
	v_mul_f32_e32 v69, v81, v81
	v_fmac_f32_e32 v69, v80, v80
	v_add_f32_e32 v68, v69, v68
	v_add_f32_e32 v71, v86, v68
	ds_bpermute_b32 v86, v120, v71
	v_ashrrev_i32_e32 v117, 31, v116
	s_waitcnt lgkmcnt(1)
	v_lshlrev_b64 v[84:85], 12, v[116:117]
	v_lshl_add_u64 v[68:69], s[16:17], 0, v[84:85]
	v_lshl_add_u64 v[84:85], v[158:159], 1, v[68:69]
	s_waitcnt lgkmcnt(0)
	v_add_f32_e32 v68, v71, v86
	ds_bpermute_b32 v69, v121, v68
	global_store_dwordx4 v[84:85], v[76:79], off
	v_cvt_pk_bf16_f32 v70, v72, v73
	v_cvt_pk_bf16_f32 v71, v74, v75
	v_cvt_pk_bf16_f32 v72, v82, v83
	v_cvt_pk_bf16_f32 v73, v80, v81
	global_store_dwordx4 v[84:85], v[70:73], off offset:256
	s_and_saveexec_b64 s[18:19], s[40:41]
	s_cbranch_execz .LBB0_574
	v_lshlrev_b64 v[70:71], 7, v[116:117]
	v_lshl_add_u64 v[70:71], s[28:29], 0, v[70:71]
	v_lshl_add_u64 v[70:71], s[0:1], 2, v[70:71]
	s_lshl_b32 s20, s53, 2
	v_lshl_add_u64 v[70:71], v[70:71], 0, s[20:21]
	s_waitcnt lgkmcnt(0)
	v_add_f32_e32 v68, v68, v69
	global_store_dword v[70:71], v68, off
; __device__ __forceinline__ unsigned cvt_pk_bf16(float lo, float hi) { unsigned r; asm volatile("v_cvt_pk_bf16_f32 %0, %1, %2" : "=v"(r) : "v"(lo), "v"(hi)); return r; }
; #define GAS __attribute__((address_space(1)))
;     __device__ __forceinline__ void operator()(const f32x4 (&acc)[2][2][4][2], const pg8::Unit& u, int wr, int wc, int fr, int fq) const {
;     ...
; #pragma unroll
;         for (int aim = 0; aim < 4; ++aim) { const int ai = aim >> 1, mb = (aim & 1) * 2;
;             f32x4 hx[4][2][2];
; #pragma unroll
;             for (int m = mb; m < mb + 2; ++m) { const int row = row0 + ai * 128 + m * 16;
;                 const GAS float* hp = (const GAS float*)x + ((size_t)(row / TSEG) * SEQ + (size_t)seg * TSEG + (row % TSEG)) * DM + col0;
; #pragma unroll
;                 for (int bj = 0; bj < 2; ++bj) { hx[m][bj][0] = __builtin_nontemporal_load((const GAS f32x4*)(hp + bj * 128)); hx[m][bj][1] = __builtin_nontemporal_load((const GAS f32x4*)(hp + bj * 128 + 4)); } }
; #pragma unroll
;             for (int m = mb; m < mb + 2; ++m) { const int row = row0 + ai * 128 + m * 16;
;                 float s = 0.f;
; #pragma unroll
;                 for (int bj = 0; bj < 2; ++bj) { const int col = col0 + bj * 128; const f32x4 v0 = acc[ai][bj][m][0] + hx[m][bj][0], v1 = acc[ai][bj][m][1] + hx[m][bj][1];
;                     v4u w; w.x = cvt_pk_bf16(v0[0], v0[1]); w.y = cvt_pk_bf16(v0[2], v0[3]); w.z = cvt_pk_bf16(v1[0], v1[1]); w.w = cvt_pk_bf16(v1[2], v1[3]);
;                     *(GAS v4u*)(h1b + (size_t)row * DM + col) = w;
;                     s += (v0[0] * v0[0] + v0[1] * v0[1]) + (v0[2] * v0[2] + v0[3] * v0[3]) + (v1[0] * v1[0] + v1[1] * v1[1]) + (v1[2] * v1[2] + v1[3] * v1[3]); }
;                 s += __shfl_xor(s, 16); s += __shfl_xor(s, 32);
;                 if (fq == 0) ssq[(size_t)row * 32 + u.pn * 4 + wc] = s; } }
.LBB0_574:
	s_or_b64 exec, exec, s[18:19]
	v_add_u32_e32 v86, 0x80, v160
	v_ashrrev_i32_e32 v87, 31, v86
	v_lshrrev_b32_e32 v68, 20, v87
	v_add_u32_e32 v68, v86, v68
	v_ashrrev_i32_e32 v68, 12, v68
	v_mul_i32_i24_e32 v70, 0x1000, v68
	s_waitcnt lgkmcnt(0)
	v_ashrrev_i32_e32 v69, 31, v68
	v_sub_u32_e32 v70, v86, v70
	v_ashrrev_i32_e32 v71, 31, v70
	v_lshlrev_b64 v[68:69], 27, v[68:69]
	v_lshlrev_b64 v[70:71], 13, v[70:71]
	v_lshl_add_u64 v[68:69], v[162:163], 0, v[68:69]
	v_lshl_add_u64 v[68:69], v[68:69], 0, v[70:71]
	s_nop 0
	s_nop 0
	s_nop 0
	s_nop 0
	v_add_u32_e32 v84, 0x90, v160
	v_ashrrev_i32_e32 v85, 31, v84
	v_lshrrev_b32_e32 v68, 20, v85
	v_add_u32_e32 v68, v84, v68
	v_ashrrev_i32_e32 v68, 12, v68
	v_mul_i32_i24_e32 v70, 0x1000, v68
	v_ashrrev_i32_e32 v69, 31, v68
	v_sub_u32_e32 v70, v84, v70
	v_lshlrev_b64 v[68:69], 27, v[68:69]
	v_ashrrev_i32_e32 v71, 31, v70
	v_lshl_add_u64 v[68:69], v[162:163], 0, v[68:69]
	v_lshlrev_b64 v[70:71], 13, v[70:71]
	v_lshl_add_u64 v[72:73], v[68:69], 0, v[70:71]
	s_nop 0
	s_nop 0
	s_nop 0
	s_nop 0
	s_nop 0
	v_lshlrev_b64 v[104:105], 12, v[86:87]
	s_waitcnt vmcnt(21)
	v_pk_add_f32 v[66:67], v[66:67], v[196:197]
	v_pk_add_f32 v[64:65], v[64:65], v[194:195]
	s_waitcnt vmcnt(18)
	v_pk_add_f32 v[58:59], v[58:59], v[146:147]
	v_pk_add_f32 v[56:57], v[56:57], v[144:145]
	v_pk_add_f32 v[62:63], v[62:63], v[186:187]
	v_pk_add_f32 v[60:61], v[60:61], v[184:185]
	s_waitcnt vmcnt(17)
	v_pk_add_f32 v[90:91], v[52:53], v[140:141]
	v_cvt_pk_bf16_f32 v52, v64, v65
	v_cvt_pk_bf16_f32 v53, v66, v67
	v_mul_f32_e32 v65, v65, v65
	v_mul_f32_e32 v67, v67, v67
	v_mul_f32_e32 v92, v57, v57
	v_mul_f32_e32 v93, v59, v59
	v_pk_add_f32 v[88:89], v[54:55], v[142:143]
	v_cvt_pk_bf16_f32 v54, v60, v61
	v_cvt_pk_bf16_f32 v55, v62, v63
	v_mul_f32_e32 v61, v61, v61
	v_mul_f32_e32 v63, v63, v63
	v_mul_f32_e32 v94, v91, v91
	v_fmac_f32_e32 v65, v64, v64
	v_fmac_f32_e32 v67, v66, v66
	v_fmac_f32_e32 v92, v56, v56
	v_fmac_f32_e32 v93, v58, v58
	v_mul_f32_e32 v95, v89, v89
	v_fmac_f32_e32 v61, v60, v60
	v_fmac_f32_e32 v63, v62, v62
	v_fmac_f32_e32 v94, v90, v90
	v_add_f32_e32 v60, v65, v67
	v_add_f32_e32 v62, v92, v93
	v_fmac_f32_e32 v95, v88, v88
	v_add_f32_e32 v60, v60, v61
	v_add_f32_e32 v61, v62, v94
	v_add_f32_e32 v60, v63, v60
	v_add_f32_e32 v61, v95, v61
	v_add_f32_e32 v62, v60, v61
	ds_bpermute_b32 v63, v120, v62
	v_lshl_add_u64 v[60:61], s[16:17], 0, v[104:105]
	v_lshl_add_u64 v[60:61], v[158:159], 1, v[60:61]
	global_store_dwordx4 v[60:61], v[52:55], off
	s_waitcnt lgkmcnt(0)
	s_nop 0
	v_add_f32_e32 v52, v62, v63
	ds_bpermute_b32 v53, v121, v52
	v_cvt_pk_bf16_f32 v54, v56, v57
	v_cvt_pk_bf16_f32 v55, v58, v59
	v_cvt_pk_bf16_f32 v56, v90, v91
	v_cvt_pk_bf16_f32 v57, v88, v89
	global_store_dwordx4 v[60:61], v[54:57], off offset:256
	s_and_saveexec_b64 s[18:19], s[40:41]
	s_cbranch_execz .LBB0_576
	v_lshlrev_b64 v[54:55], 7, v[86:87]
	v_lshl_add_u64 v[54:55], s[28:29], 0, v[54:55]
	v_lshl_add_u64 v[54:55], s[0:1], 2, v[54:55]
	s_lshl_b32 s20, s53, 2
	v_lshl_add_u64 v[54:55], v[54:55], 0, s[20:21]
	s_waitcnt lgkmcnt(0)
	v_add_f32_e32 v52, v52, v53
	global_store_dword v[54:55], v52, off
.LBB0_576:
	s_or_b64 exec, exec, s[18:19]
	s_waitcnt vmcnt(16)
	v_pk_add_f32 v[48:49], v[48:49], v[130:131]
	v_pk_add_f32 v[50:51], v[50:51], v[132:133]
	v_pk_add_f32 v[56:57], v[44:45], v[134:135]
	v_cvt_pk_bf16_f32 v44, v48, v49
	v_mul_f32_e32 v49, v49, v49
	v_fmac_f32_e32 v49, v48, v48
	v_mul_f32_e32 v48, v51, v51
	v_fmac_f32_e32 v48, v50, v50
	v_add_f32_e32 v48, v49, v48
	v_mul_f32_e32 v49, v57, v57
	s_waitcnt vmcnt(14)
	v_pk_add_f32 v[42:43], v[42:43], v[114:115]
	v_pk_add_f32 v[40:41], v[40:41], v[112:113]
	v_pk_add_f32 v[54:55], v[46:47], v[136:137]
	v_cvt_pk_bf16_f32 v45, v50, v51
	v_fmac_f32_e32 v49, v56, v56
	v_pk_add_f32 v[50:51], v[36:37], v[108:109]
	v_mul_f32_e32 v36, v41, v41
	v_mul_f32_e32 v37, v43, v43
	v_add_f32_e32 v48, v48, v49
	v_mul_f32_e32 v49, v55, v55
	v_fmac_f32_e32 v36, v40, v40
	v_fmac_f32_e32 v37, v42, v42
	v_fmac_f32_e32 v49, v54, v54
	v_add_f32_e32 v36, v36, v37
	v_mul_f32_e32 v37, v51, v51
	v_cvt_pk_bf16_f32 v46, v56, v57
	v_cvt_pk_bf16_f32 v47, v54, v55
	v_add_f32_e32 v54, v49, v48
	v_pk_add_f32 v[48:49], v[38:39], v[110:111]
	v_fmac_f32_e32 v37, v50, v50
	v_add_f32_e32 v36, v36, v37
	v_mul_f32_e32 v37, v49, v49
	v_fmac_f32_e32 v37, v48, v48
	v_add_f32_e32 v36, v37, v36
	v_add_f32_e32 v39, v54, v36
	ds_bpermute_b32 v54, v120, v39
	s_waitcnt lgkmcnt(1)
	v_lshlrev_b64 v[52:53], 12, v[84:85]
	v_lshl_add_u64 v[36:37], s[16:17], 0, v[52:53]
	v_lshl_add_u64 v[52:53], v[158:159], 1, v[36:37]
	global_store_dwordx4 v[52:53], v[44:47], off
	s_waitcnt lgkmcnt(0)
	v_add_f32_e32 v36, v39, v54
	ds_bpermute_b32 v37, v121, v36
	v_cvt_pk_bf16_f32 v38, v40, v41
	v_cvt_pk_bf16_f32 v39, v42, v43
	v_cvt_pk_bf16_f32 v40, v50, v51
	v_cvt_pk_bf16_f32 v41, v48, v49
	global_store_dwordx4 v[52:53], v[38:41], off offset:256
	s_and_saveexec_b64 s[18:19], s[40:41]
	s_cbranch_execz .LBB0_578
	v_lshlrev_b64 v[38:39], 7, v[84:85]
	v_lshl_add_u64 v[38:39], s[28:29], 0, v[38:39]
	v_lshl_add_u64 v[38:39], s[0:1], 2, v[38:39]
	s_lshl_b32 s20, s53, 2
	v_lshl_add_u64 v[38:39], v[38:39], 0, s[20:21]
	s_waitcnt lgkmcnt(0)
	v_add_f32_e32 v36, v36, v37
	global_store_dword v[38:39], v36, off
; __device__ __forceinline__ unsigned cvt_pk_bf16(float lo, float hi) { unsigned r; asm volatile("v_cvt_pk_bf16_f32 %0, %1, %2" : "=v"(r) : "v"(lo), "v"(hi)); return r; }
; #define GAS __attribute__((address_space(1)))
;     __device__ __forceinline__ void operator()(const f32x4 (&acc)[2][2][4][2], const pg8::Unit& u, int wr, int wc, int fr, int fq) const {
;     ...
; #pragma unroll
;         for (int aim = 0; aim < 4; ++aim) { const int ai = aim >> 1, mb = (aim & 1) * 2;
;             f32x4 hx[4][2][2];
; #pragma unroll
;             for (int m = mb; m < mb + 2; ++m) { const int row = row0 + ai * 128 + m * 16;
;                 const GAS float* hp = (const GAS float*)x + ((size_t)(row / TSEG) * SEQ + (size_t)seg * TSEG + (row % TSEG)) * DM + col0;
; #pragma unroll
;                 for (int bj = 0; bj < 2; ++bj) { hx[m][bj][0] = __builtin_nontemporal_load((const GAS f32x4*)(hp + bj * 128)); hx[m][bj][1] = __builtin_nontemporal_load((const GAS f32x4*)(hp + bj * 128 + 4)); } }
; #pragma unroll
;             for (int m = mb; m < mb + 2; ++m) { const int row = row0 + ai * 128 + m * 16;
;                 float s = 0.f;
; #pragma unroll
;                 for (int bj = 0; bj < 2; ++bj) { const int col = col0 + bj * 128; const f32x4 v0 = acc[ai][bj][m][0] + hx[m][bj][0], v1 = acc[ai][bj][m][1] + hx[m][bj][1];
;                     v4u w; w.x = cvt_pk_bf16(v0[0], v0[1]); w.y = cvt_pk_bf16(v0[2], v0[3]); w.z = cvt_pk_bf16(v1[0], v1[1]); w.w = cvt_pk_bf16(v1[2], v1[3]);
;                     *(GAS v4u*)(h1b + (size_t)row * DM + col) = w;
;                     s += (v0[0] * v0[0] + v0[1] * v0[1]) + (v0[2] * v0[2] + v0[3] * v0[3]) + (v1[0] * v1[0] + v1[1] * v1[1]) + (v1[2] * v1[2] + v1[3] * v1[3]); }
;                 s += __shfl_xor(s, 16); s += __shfl_xor(s, 32);
;                 if (fq == 0) ssq[(size_t)row * 32 + u.pn * 4 + wc] = s; } }
.LBB0_578:
	s_or_b64 exec, exec, s[18:19]
	v_add_u32_e32 v54, 0xa0, v160
	v_ashrrev_i32_e32 v55, 31, v54
	v_lshrrev_b32_e32 v36, 20, v55
	v_add_u32_e32 v36, v54, v36
	v_ashrrev_i32_e32 v36, 12, v36
	v_mul_i32_i24_e32 v38, 0x1000, v36
	s_waitcnt lgkmcnt(0)
	v_ashrrev_i32_e32 v37, 31, v36
	v_sub_u32_e32 v38, v54, v38
	v_ashrrev_i32_e32 v39, 31, v38
	v_lshlrev_b64 v[36:37], 27, v[36:37]
	v_lshlrev_b64 v[38:39], 13, v[38:39]
	v_lshl_add_u64 v[36:37], v[162:163], 0, v[36:37]
	v_lshl_add_u64 v[36:37], v[36:37], 0, v[38:39]
	s_nop 0
	s_nop 0
	s_nop 0
	s_nop 0
	v_add_u32_e32 v52, 0xb0, v160
	v_ashrrev_i32_e32 v53, 31, v52
	v_lshrrev_b32_e32 v36, 20, v53
	v_add_u32_e32 v36, v52, v36
	v_ashrrev_i32_e32 v36, 12, v36
	v_mul_i32_i24_e32 v38, 0x1000, v36
	v_ashrrev_i32_e32 v37, 31, v36
	v_sub_u32_e32 v38, v52, v38
	v_lshlrev_b64 v[36:37], 27, v[36:37]
	v_ashrrev_i32_e32 v39, 31, v38
	v_lshl_add_u64 v[36:37], v[162:163], 0, v[36:37]
	v_lshlrev_b64 v[38:39], 13, v[38:39]
	v_lshl_add_u64 v[40:41], v[36:37], 0, v[38:39]
	s_nop 0
	s_nop 0
	s_nop 0
	s_nop 0
	s_nop 0
	v_lshlrev_b64 v[72:73], 12, v[54:55]
	s_waitcnt vmcnt(14)
	v_pk_add_f32 v[34:35], v[34:35], v[224:225]
	v_pk_add_f32 v[32:33], v[32:33], v[222:223]
	s_waitcnt vmcnt(12)
	v_pk_add_f32 v[26:27], v[26:27], v[216:217]
	v_pk_add_f32 v[24:25], v[24:25], v[214:215]
	v_pk_add_f32 v[30:31], v[30:31], v[220:221]
	v_pk_add_f32 v[28:29], v[28:29], v[218:219]
	s_waitcnt vmcnt(11)
	v_pk_add_f32 v[58:59], v[20:21], v[210:211]
	v_cvt_pk_bf16_f32 v20, v32, v33
	v_cvt_pk_bf16_f32 v21, v34, v35
	v_mul_f32_e32 v33, v33, v33
	v_mul_f32_e32 v35, v35, v35
	v_mul_f32_e32 v60, v25, v25
	v_mul_f32_e32 v61, v27, v27
	v_pk_add_f32 v[56:57], v[22:23], v[212:213]
	v_cvt_pk_bf16_f32 v22, v28, v29
	v_cvt_pk_bf16_f32 v23, v30, v31
	v_mul_f32_e32 v29, v29, v29
	v_mul_f32_e32 v31, v31, v31
	v_mul_f32_e32 v62, v59, v59
	v_fmac_f32_e32 v33, v32, v32
	v_fmac_f32_e32 v35, v34, v34
	v_fmac_f32_e32 v60, v24, v24
	v_fmac_f32_e32 v61, v26, v26
	v_mul_f32_e32 v63, v57, v57
	v_fmac_f32_e32 v29, v28, v28
	v_fmac_f32_e32 v31, v30, v30
	v_fmac_f32_e32 v62, v58, v58
	v_add_f32_e32 v28, v33, v35
	v_add_f32_e32 v30, v60, v61
	v_fmac_f32_e32 v63, v56, v56
	v_add_f32_e32 v28, v28, v29
	v_add_f32_e32 v29, v30, v62
	v_add_f32_e32 v28, v31, v28
	v_add_f32_e32 v29, v63, v29
	v_add_f32_e32 v30, v28, v29
	ds_bpermute_b32 v31, v120, v30
	v_lshl_add_u64 v[28:29], s[16:17], 0, v[72:73]
	v_lshl_add_u64 v[28:29], v[158:159], 1, v[28:29]
	global_store_dwordx4 v[28:29], v[20:23], off
	s_waitcnt lgkmcnt(0)
	s_nop 0
	v_add_f32_e32 v20, v30, v31
	ds_bpermute_b32 v21, v121, v20
	v_cvt_pk_bf16_f32 v22, v24, v25
	v_cvt_pk_bf16_f32 v23, v26, v27
	v_cvt_pk_bf16_f32 v24, v58, v59
	v_cvt_pk_bf16_f32 v25, v56, v57
	global_store_dwordx4 v[28:29], v[22:25], off offset:256
	s_and_saveexec_b64 s[18:19], s[40:41]
	s_cbranch_execz .LBB0_580
	v_lshlrev_b64 v[22:23], 7, v[54:55]
	v_lshl_add_u64 v[22:23], s[28:29], 0, v[22:23]
	v_lshl_add_u64 v[22:23], s[0:1], 2, v[22:23]
	s_lshl_b32 s20, s53, 2
	v_lshl_add_u64 v[22:23], v[22:23], 0, s[20:21]
	s_waitcnt lgkmcnt(0)
	v_add_f32_e32 v20, v20, v21
	global_store_dword v[22:23], v20, off
.LBB0_580:
	s_or_b64 exec, exec, s[18:19]
	s_waitcnt vmcnt(10)
	v_pk_add_f32 v[16:17], v[16:17], v[100:101]
	v_pk_add_f32 v[18:19], v[18:19], v[102:103]
	v_pk_add_f32 v[24:25], v[12:13], v[126:127]
	v_cvt_pk_bf16_f32 v12, v16, v17
	v_mul_f32_e32 v17, v17, v17
	v_fmac_f32_e32 v17, v16, v16
	v_mul_f32_e32 v16, v19, v19
	v_fmac_f32_e32 v16, v18, v18
	v_add_f32_e32 v16, v17, v16
	v_mul_f32_e32 v17, v25, v25
	s_waitcnt vmcnt(8)
	v_pk_add_f32 v[10:11], v[10:11], v[124:125]
	v_pk_add_f32 v[8:9], v[8:9], v[122:123]
	v_pk_add_f32 v[22:23], v[14:15], v[128:129]
	v_cvt_pk_bf16_f32 v13, v18, v19
	v_fmac_f32_e32 v17, v24, v24
	v_pk_add_f32 v[18:19], v[4:5], v[96:97]
	v_mul_f32_e32 v4, v9, v9
	v_mul_f32_e32 v5, v11, v11
	v_add_f32_e32 v16, v16, v17
	v_mul_f32_e32 v17, v23, v23
	v_fmac_f32_e32 v4, v8, v8
	v_fmac_f32_e32 v5, v10, v10
	v_fmac_f32_e32 v17, v22, v22
	v_add_f32_e32 v4, v4, v5
	v_mul_f32_e32 v5, v19, v19
	v_cvt_pk_bf16_f32 v14, v24, v25
	v_cvt_pk_bf16_f32 v15, v22, v23
	v_add_f32_e32 v22, v17, v16
	v_pk_add_f32 v[16:17], v[6:7], v[98:99]
	v_fmac_f32_e32 v5, v18, v18
	v_add_f32_e32 v4, v4, v5
	v_mul_f32_e32 v5, v17, v17
	v_fmac_f32_e32 v5, v16, v16
	v_add_f32_e32 v4, v5, v4
	v_add_f32_e32 v7, v22, v4
	ds_bpermute_b32 v22, v120, v7
	s_waitcnt lgkmcnt(1)
	v_lshlrev_b64 v[20:21], 12, v[52:53]
	v_lshl_add_u64 v[4:5], s[16:17], 0, v[20:21]
	v_lshl_add_u64 v[20:21], v[158:159], 1, v[4:5]
	global_store_dwordx4 v[20:21], v[12:15], off
	s_waitcnt lgkmcnt(0)
	v_add_f32_e32 v4, v7, v22
	ds_bpermute_b32 v5, v121, v4
	v_cvt_pk_bf16_f32 v6, v8, v9
	v_cvt_pk_bf16_f32 v7, v10, v11
	v_cvt_pk_bf16_f32 v8, v18, v19
	v_cvt_pk_bf16_f32 v9, v16, v17
	global_store_dwordx4 v[20:21], v[6:9], off offset:256
	s_and_saveexec_b64 s[18:19], s[40:41]
	s_cbranch_execz .LBB0_582
	v_lshlrev_b64 v[6:7], 7, v[52:53]
	v_lshl_add_u64 v[6:7], s[28:29], 0, v[6:7]
	v_lshl_add_u64 v[6:7], s[0:1], 2, v[6:7]
	s_lshl_b32 s20, s53, 2
	v_lshl_add_u64 v[6:7], v[6:7], 0, s[20:21]
	s_waitcnt lgkmcnt(0)
	v_add_f32_e32 v4, v4, v5
	global_store_dword v[6:7], v4, off

; #define GAS __attribute__((address_space(1)))
;     __device__ __forceinline__ void operator()(const f32x4 (&acc)[2][2][4][2], const pg8::Unit& u, int wr, int wc, int fr, int fq) const {
;     ...
; #pragma unroll
;         for (int aim = 0; aim < 4; ++aim) { const int ai = aim >> 1, mb = (aim & 1) * 2;
;             v4u hr[4][2];
; #pragma unroll
;             for (int m = mb; m < mb + 2; ++m) { const GAS bf16* hp = h1 + (size_t)(row0 + ai * 128 + m * 16) * DM + col0;
; #pragma unroll
;                 for (int bj = 0; bj < 2; ++bj) hr[m][bj] = *(const GAS v4u*)(hp + bj * 128); }
.LBB0_825:
	v_lshl_or_b32 v150, s20, 8, v160
	v_lshl_add_u32 v152, s22, 8, v158
	v_ashrrev_i32_e32 v151, 31, v150
	v_lshlrev_b64 v[170:171], 1, v[150:151]
	v_ashrrev_i32_e32 v153, 31, v152
	v_lshl_add_u64 v[154:155], s[42:43], 0, v[170:171]
	v_lshlrev_b64 v[116:117], 12, v[152:153]
	v_lshl_add_u64 v[116:117], v[154:155], 0, v[116:117]
	global_load_dwordx4 v[162:165], v[116:117], off
	global_load_dwordx4 v[166:169], v[116:117], off offset:256
	v_or_b32_e32 v156, 16, v152
	v_ashrrev_i32_e32 v157, 31, v156
	v_lshlrev_b64 v[116:117], 12, v[156:157]
	v_lshl_add_u64 v[116:117], v[154:155], 0, v[116:117]
	global_load_dwordx4 v[120:123], v[116:117], off
	s_nop 0
	global_load_dwordx4 v[116:119], v[116:117], off offset:256
	s_nop 1
	v_or_b32_e32 v251, 32, v152
	v_ashrrev_i32_e32 v250, 31, v251
	v_mov_b32_e32 v246, v251
	v_mov_b32_e32 v247, v250
	v_lshlrev_b64 v[248:249], 12, v[246:247]
	v_lshl_add_u64 v[244:245], v[154:155], 0, v[248:249]
	global_load_dwordx4 v[234:237], v[244:245], off
	v_or_b32_e32 v251, 32, v152
	v_ashrrev_i32_e32 v250, 31, v251
	v_mov_b32_e32 v246, v251
	v_mov_b32_e32 v247, v250
	v_lshlrev_b64 v[248:249], 12, v[246:247]
	v_lshl_add_u64 v[244:245], v[154:155], 0, v[248:249]
	global_load_dwordx4 v[230:233], v[244:245], off offset:256
	v_or_b32_e32 v251, 48, v152
	v_ashrrev_i32_e32 v250, 31, v251
	v_mov_b32_e32 v246, v251
	v_mov_b32_e32 v247, v250
	v_lshlrev_b64 v[248:249], 12, v[246:247]
	v_lshl_add_u64 v[244:245], v[154:155], 0, v[248:249]
	global_load_dwordx4 v[226:229], v[244:245], off
	v_or_b32_e32 v251, 48, v152
	v_ashrrev_i32_e32 v250, 31, v251
	v_mov_b32_e32 v246, v251
	v_mov_b32_e32 v247, v250
	v_lshlrev_b64 v[248:249], 12, v[246:247]
	v_lshl_add_u64 v[244:245], v[154:155], 0, v[248:249]
	global_load_dwordx4 v[222:225], v[244:245], off offset:256
	v_add_u32_e32 v251, 0x80, v152
	v_ashrrev_i32_e32 v250, 31, v251
	v_mov_b32_e32 v246, v251
	v_mov_b32_e32 v247, v250
	v_lshlrev_b64 v[248:249], 12, v[246:247]
	v_lshl_add_u64 v[244:245], v[154:155], 0, v[248:249]
	global_load_dwordx4 v[218:221], v[244:245], off
	v_add_u32_e32 v251, 0x80, v152
	v_ashrrev_i32_e32 v250, 31, v251
	v_mov_b32_e32 v246, v251
	v_mov_b32_e32 v247, v250
	v_lshlrev_b64 v[248:249], 12, v[246:247]
	v_lshl_add_u64 v[244:245], v[154:155], 0, v[248:249]
	global_load_dwordx4 v[214:217], v[244:245], off offset:256
	v_add_u32_e32 v251, 0x90, v152
	v_ashrrev_i32_e32 v250, 31, v251
	v_mov_b32_e32 v246, v251
	v_mov_b32_e32 v247, v250
	v_lshlrev_b64 v[248:249], 12, v[246:247]
	v_lshl_add_u64 v[244:245], v[154:155], 0, v[248:249]
	global_load_dwordx4 v[210:213], v[244:245], off
	v_add_u32_e32 v251, 0x90, v152
	v_ashrrev_i32_e32 v250, 31, v251
	v_mov_b32_e32 v246, v251
	v_mov_b32_e32 v247, v250
	v_lshlrev_b64 v[248:249], 12, v[246:247]
	v_lshl_add_u64 v[244:245], v[154:155], 0, v[248:249]
	global_load_dwordx4 v[206:209], v[244:245], off offset:256
	v_add_u32_e32 v251, 0xa0, v152
	v_ashrrev_i32_e32 v250, 31, v251
	v_mov_b32_e32 v246, v251
	v_mov_b32_e32 v247, v250
	v_lshlrev_b64 v[248:249], 12, v[246:247]
	v_lshl_add_u64 v[244:245], v[154:155], 0, v[248:249]
	global_load_dwordx4 v[202:205], v[244:245], off
	v_add_u32_e32 v251, 0xa0, v152
	v_ashrrev_i32_e32 v250, 31, v251
	v_mov_b32_e32 v246, v251
	v_mov_b32_e32 v247, v250
	v_lshlrev_b64 v[248:249], 12, v[246:247]
	v_lshl_add_u64 v[244:245], v[154:155], 0, v[248:249]
	global_load_dwordx4 v[198:201], v[244:245], off offset:256
	v_add_u32_e32 v251, 0xb0, v152
	v_ashrrev_i32_e32 v250, 31, v251
	v_mov_b32_e32 v246, v251
	v_mov_b32_e32 v247, v250
	v_lshlrev_b64 v[248:249], 12, v[246:247]
	v_lshl_add_u64 v[244:245], v[154:155], 0, v[248:249]
	global_load_dwordx4 v[194:197], v[244:245], off
	v_add_u32_e32 v251, 0xb0, v152
	v_ashrrev_i32_e32 v250, 31, v251
	v_mov_b32_e32 v246, v251
	v_mov_b32_e32 v247, v250
	v_lshlrev_b64 v[248:249], 12, v[246:247]
	v_lshl_add_u64 v[244:245], v[154:155], 0, v[248:249]
	global_load_dwordx4 v[190:193], v[244:245], off offset:256
	v_lshrrev_b32_e32 v179, 20, v153
	v_add_u32_e32 v179, v152, v179
	v_ashrrev_i32_e32 v184, 12, v179
	v_mul_i32_i24_e32 v179, 0x1000, v184
	v_ashrrev_i32_e32 v185, 31, v184
	v_sub_u32_e32 v186, v152, v179
	v_ashrrev_i32_e32 v187, 31, v186
	v_lshlrev_b64 v[184:185], 27, v[184:185]
	v_lshlrev_b64 v[186:187], 13, v[186:187]
	v_lshl_add_u64 v[184:185], s[44:45], 0, v[184:185]
	v_lshl_add_u64 v[184:185], v[184:185], 0, v[186:187]
	v_lshl_add_u64 v[170:171], v[184:185], 0, v[170:171]
	s_lshl_b32 s14, s20, 2
	s_ashr_i32 s15, s14, 31
	s_waitcnt vmcnt(12)
; __device__ __forceinline__ unsigned cvt_pk_bf16(float lo, float hi) { unsigned r; asm volatile("v_cvt_pk_bf16_f32 %0, %1, %2" : "=v"(r) : "v"(lo), "v"(hi)); return r; }
; #define GAS __attribute__((address_space(1)))
; __device__ __forceinline__ void unpack8(const v4u v, float (&f)[8]) { f[0] = bflo(v.x); f[1] = bfhi(v.x); f[2] = bflo(v.y); f[3] = bfhi(v.y); f[4] = bflo(v.z); f[5] = bfhi(v.z); f[6] = bflo(v.w); f[7] = bfhi(v.w); }
;     __device__ __forceinline__ void operator()(const f32x4 (&acc)[2][2][4][2], const pg8::Unit& u, int wr, int wc, int fr, int fq) const {
;     ...
;             for (int m = mb; m < mb + 2; ++m) { const int row = row0 + ai * 128 + m * 16;
;                 GAS bf16* op = (GAS bf16*)((GAS float*)out + ((size_t)(row / TSEG) * SEQ + (size_t)seg * TSEG + (row % TSEG)) * DM);
;                 float s = 0.f;
; #pragma unroll
;                 for (int bj = 0; bj < 2; ++bj) { const int col = col0 + bj * 128; float hf[8]; unpack8(hr[m][bj], hf);
;                     const f32x4 v0 = acc[ai][bj][m][0] + (f32x4){hf[0], hf[1], hf[2], hf[3]}, v1 = acc[ai][bj][m][1] + (f32x4){hf[4], hf[5], hf[6], hf[7]};
;                     { v4u w; w.x = cvt_pk_bf16(v0[0], v0[1]); w.y = cvt_pk_bf16(v0[2], v0[3]); w.z = cvt_pk_bf16(v1[0], v1[1]); w.w = cvt_pk_bf16(v1[2], v1[3]); __builtin_nontemporal_store(w, (GAS v4u*)(op + col)); }
;                     s += (v0[0] * v0[0] + v0[1] * v0[1]) + (v0[2] * v0[2] + v0[3] * v0[3]) + (v1[0] * v1[0] + v1[1] * v1[1]) + (v1[2] * v1[2] + v1[3] * v1[3]); }
;                 s += __shfl_xor(s, 16); s += __shfl_xor(s, 32);
;                 if (fq == 0) ssq[((size_t)seg * RS + row) * 32 + u.pn * 4 + wc] = s; } }
	v_lshlrev_b32_e32 v186, 16, v162
	v_and_b32_e32 v187, 0xffff0000, v162
	v_lshlrev_b32_e32 v162, 16, v163
	v_and_b32_e32 v163, 0xffff0000, v163
	v_lshlrev_b32_e32 v188, 16, v164
	v_and_b32_e32 v189, 0xffff0000, v164
	v_lshlrev_b32_e32 v164, 16, v165
	v_and_b32_e32 v165, 0xffff0000, v165
	v_pk_add_f32 v[138:139], v[138:139], v[162:163]
	v_pk_add_f32 v[136:137], v[136:137], v[186:187]
	v_pk_add_f32 v[162:163], v[134:135], v[164:165]
	v_pk_add_f32 v[164:165], v[132:133], v[188:189]
	v_cvt_pk_bf16_f32 v132, v136, v137
	v_cvt_pk_bf16_f32 v133, v138, v139
	s_nop 0
	v_cvt_pk_bf16_f32 v134, v164, v165
	v_cvt_pk_bf16_f32 v135, v162, v163
	global_store_dwordx4 v[170:171], v[132:135], off nt
	s_nop 1
	v_mul_f32_e32 v132, v137, v137
	v_mul_f32_e32 v133, v139, v139
	v_fmac_f32_e32 v132, v136, v136
	v_fmac_f32_e32 v133, v138, v138
	v_add_f32_e32 v132, v132, v133
	v_mul_f32_e32 v133, v165, v165
	v_fmac_f32_e32 v133, v164, v164
	v_add_f32_e32 v132, v133, v132
	v_mul_f32_e32 v133, v163, v163
	v_fmac_f32_e32 v133, v162, v162
	v_add_f32_e32 v162, v133, v132
	v_lshlrev_b32_e32 v132, 16, v166
	v_and_b32_e32 v133, 0xffff0000, v166
	v_lshlrev_b32_e32 v134, 16, v167
	v_and_b32_e32 v135, 0xffff0000, v167
	v_lshlrev_b32_e32 v136, 16, v168
	v_and_b32_e32 v137, 0xffff0000, v168
	v_lshlrev_b32_e32 v138, 16, v169
	v_and_b32_e32 v139, 0xffff0000, v169
	v_pk_add_f32 v[130:131], v[130:131], v[134:135]
	v_pk_add_f32 v[128:129], v[128:129], v[132:133]
	v_pk_add_f32 v[134:135], v[124:125], v[136:137]
	v_cvt_pk_bf16_f32 v124, v128, v129
	v_cvt_pk_bf16_f32 v125, v130, v131
	v_pk_add_f32 v[132:133], v[126:127], v[138:139]
	v_cvt_pk_bf16_f32 v126, v134, v135
	s_nop 0
	v_cvt_pk_bf16_f32 v127, v132, v133
	global_store_dwordx4 v[170:171], v[124:127], off offset:256 nt
	s_nop 1
	v_mul_f32_e32 v124, v129, v129
	v_mul_f32_e32 v125, v131, v131
	v_fmac_f32_e32 v124, v128, v128
	v_fmac_f32_e32 v125, v130, v130
	v_add_f32_e32 v124, v124, v125
	v_mul_f32_e32 v125, v135, v135
	v_fmac_f32_e32 v125, v134, v134
	v_add_f32_e32 v124, v125, v124
	v_mul_f32_e32 v125, v133, v133
	v_fmac_f32_e32 v125, v132, v132
	v_add_f32_e32 v124, v125, v124
	v_and_b32_e32 v126, 64, v173
	v_add_f32_e32 v125, v162, v124
	v_xor_b32_e32 v124, 16, v173
	v_add_u32_e32 v127, 64, v126
	v_cmp_lt_i32_e32 vcc, v124, v127
	s_nop 1
	v_cndmask_b32_e32 v124, v173, v124, vcc
	v_lshlrev_b32_e32 v124, 2, v124
	ds_bpermute_b32 v126, v124, v125
	s_waitcnt lgkmcnt(0)
	v_add_f32_e32 v126, v125, v126
	v_xor_b32_e32 v125, 32, v173
	v_cmp_lt_i32_e32 vcc, v125, v127
	s_nop 1
	v_cndmask_b32_e32 v125, v173, v125, vcc
	v_lshlrev_b32_e32 v125, 2, v125
	ds_bpermute_b32 v127, v125, v126
	s_and_saveexec_b64 s[0:1], s[36:37]
	s_cbranch_execz .LBB0_827
	s_waitcnt lgkmcnt(0)
	v_add_f32_e32 v128, v126, v127
	v_lshlrev_b64 v[126:127], 7, v[152:153]
	v_lshl_add_u64 v[126:127], s[46:47], 0, v[126:127]
	v_lshl_add_u64 v[126:127], s[14:15], 2, v[126:127]
	s_lshl_b32 s20, s53, 2
	v_lshl_add_u64 v[126:127], v[126:127], 0, s[20:21]
	global_store_dword v[126:127], v128, off

; __device__ __forceinline__ unsigned cvt_pk_bf16(float lo, float hi) { unsigned r; asm volatile("v_cvt_pk_bf16_f32 %0, %1, %2" : "=v"(r) : "v"(lo), "v"(hi)); return r; }
; #define GAS __attribute__((address_space(1)))
; __device__ __forceinline__ void unpack8(const v4u v, float (&f)[8]) { f[0] = bflo(v.x); f[1] = bfhi(v.x); f[2] = bflo(v.y); f[3] = bfhi(v.y); f[4] = bflo(v.z); f[5] = bfhi(v.z); f[6] = bflo(v.w); f[7] = bfhi(v.w); }
;     __device__ __forceinline__ void operator()(const f32x4 (&acc)[2][2][4][2], const pg8::Unit& u, int wr, int wc, int fr, int fq) const {
;     ...
; #pragma unroll
;         for (int aim = 0; aim < 4; ++aim) { const int ai = aim >> 1, mb = (aim & 1) * 2;
;             v4u hr[4][2];
; #pragma unroll
;             for (int m = mb; m < mb + 2; ++m) { const GAS bf16* hp = h1 + (size_t)(row0 + ai * 128 + m * 16) * DM + col0;
; #pragma unroll
;                 for (int bj = 0; bj < 2; ++bj) hr[m][bj] = *(const GAS v4u*)(hp + bj * 128); }
; #pragma unroll
;             for (int m = mb; m < mb + 2; ++m) { const int row = row0 + ai * 128 + m * 16;
;                 GAS bf16* op = (GAS bf16*)((GAS float*)out + ((size_t)(row / TSEG) * SEQ + (size_t)seg * TSEG + (row % TSEG)) * DM);
;                 float s = 0.f;
; #pragma unroll
;                 for (int bj = 0; bj < 2; ++bj) { const int col = col0 + bj * 128; float hf[8]; unpack8(hr[m][bj], hf);
;                     const f32x4 v0 = acc[ai][bj][m][0] + (f32x4){hf[0], hf[1], hf[2], hf[3]}, v1 = acc[ai][bj][m][1] + (f32x4){hf[4], hf[5], hf[6], hf[7]};
;                     { v4u w; w.x = cvt_pk_bf16(v0[0], v0[1]); w.y = cvt_pk_bf16(v0[2], v0[3]); w.z = cvt_pk_bf16(v1[0], v1[1]); w.w = cvt_pk_bf16(v1[2], v1[3]); __builtin_nontemporal_store(w, (GAS v4u*)(op + col)); }
;                     s += (v0[0] * v0[0] + v0[1] * v0[1]) + (v0[2] * v0[2] + v0[3] * v0[3]) + (v1[0] * v1[0] + v1[1] * v1[1]) + (v1[2] * v1[2] + v1[3] * v1[3]); }
;                 s += __shfl_xor(s, 16); s += __shfl_xor(s, 32);
;                 if (fq == 0) ssq[((size_t)seg * RS + row) * 32 + u.pn * 4 + wc] = s; } }
.LBB0_829:
	s_or_b64 exec, exec, s[0:1]
	v_or_b32_e32 v110, 32, v152
	v_ashrrev_i32_e32 v111, 31, v110
	s_waitcnt lgkmcnt(0)
	v_lshlrev_b64 v[100:101], 12, v[110:111]
	v_lshl_add_u64 v[100:101], v[154:155], 0, v[100:101]
	s_nop 0
	s_nop 0
	v_or_b32_e32 v108, 48, v152
	v_ashrrev_i32_e32 v109, 31, v108
	v_lshlrev_b64 v[100:101], 12, v[108:109]
	v_lshl_add_u64 v[100:101], v[154:155], 0, v[100:101]
	s_nop 0
	s_nop 0
	s_nop 0
	v_ashrrev_i32_e32 v120, 31, v152
	v_lshrrev_b32_e32 v120, 20, v120
	v_add_u32_e32 v120, v110, v120
	v_ashrrev_i32_e32 v120, 12, v120
	v_mul_i32_i24_e32 v122, 0x1000, v120
	v_ashrrev_i32_e32 v121, 31, v120
	v_sub_u32_e32 v122, v110, v122
	v_ashrrev_i32_e32 v123, 31, v122
	v_lshlrev_b64 v[120:121], 27, v[120:121]
	v_lshlrev_b64 v[122:123], 13, v[122:123]
	v_lshl_add_u64 v[120:121], s[44:45], 0, v[120:121]
	v_lshl_add_u64 v[120:121], v[120:121], 0, v[122:123]
	v_lshl_add_u64 v[120:121], v[150:151], 1, v[120:121]
	s_waitcnt vmcnt(15)
	v_lshlrev_b32_e32 v122, 16, v234
	v_and_b32_e32 v123, 0xffff0000, v234
	v_lshlrev_b32_e32 v112, 16, v235
	v_and_b32_e32 v113, 0xffff0000, v235
	v_lshlrev_b32_e32 v126, 16, v236
	v_and_b32_e32 v127, 0xffff0000, v236
	v_lshlrev_b32_e32 v114, 16, v237
	v_and_b32_e32 v115, 0xffff0000, v237
	v_pk_add_f32 v[98:99], v[98:99], v[112:113]
	v_pk_add_f32 v[96:97], v[96:97], v[122:123]
	v_pk_add_f32 v[112:113], v[94:95], v[114:115]
	v_pk_add_f32 v[114:115], v[92:93], v[126:127]
	v_cvt_pk_bf16_f32 v92, v96, v97
	v_cvt_pk_bf16_f32 v93, v98, v99
	s_nop 0
	v_cvt_pk_bf16_f32 v94, v114, v115
	v_cvt_pk_bf16_f32 v95, v112, v113
	global_store_dwordx4 v[120:121], v[92:95], off nt
	s_nop 1
	v_mul_f32_e32 v92, v97, v97
	v_mul_f32_e32 v93, v99, v99
	v_fmac_f32_e32 v92, v96, v96
	v_fmac_f32_e32 v93, v98, v98
	v_add_f32_e32 v92, v92, v93
	v_mul_f32_e32 v93, v115, v115
	v_fmac_f32_e32 v93, v114, v114
	v_add_f32_e32 v92, v93, v92
	v_mul_f32_e32 v93, v113, v113
	v_fmac_f32_e32 v93, v112, v112
	v_add_f32_e32 v112, v93, v92
	s_waitcnt vmcnt(15)
	v_lshlrev_b32_e32 v92, 16, v230
	v_and_b32_e32 v93, 0xffff0000, v230
	v_lshlrev_b32_e32 v94, 16, v231
	v_and_b32_e32 v95, 0xffff0000, v231
	v_lshlrev_b32_e32 v96, 16, v232
	v_and_b32_e32 v97, 0xffff0000, v232
	v_lshlrev_b32_e32 v98, 16, v233
	v_and_b32_e32 v99, 0xffff0000, v233
	v_pk_add_f32 v[90:91], v[90:91], v[94:95]
	v_pk_add_f32 v[88:89], v[88:89], v[92:93]
	v_pk_add_f32 v[94:95], v[84:85], v[96:97]
	v_cvt_pk_bf16_f32 v84, v88, v89
	v_cvt_pk_bf16_f32 v85, v90, v91
	v_pk_add_f32 v[92:93], v[86:87], v[98:99]
	v_cvt_pk_bf16_f32 v86, v94, v95
	s_nop 0
	v_cvt_pk_bf16_f32 v87, v92, v93
	global_store_dwordx4 v[120:121], v[84:87], off offset:256 nt
	s_nop 1
	v_mul_f32_e32 v84, v89, v89
	v_mul_f32_e32 v85, v91, v91
	v_fmac_f32_e32 v84, v88, v88
	v_fmac_f32_e32 v85, v90, v90
	v_add_f32_e32 v84, v84, v85
	v_mul_f32_e32 v85, v95, v95
	v_fmac_f32_e32 v85, v94, v94
	v_add_f32_e32 v84, v85, v84
	v_mul_f32_e32 v85, v93, v93
	v_fmac_f32_e32 v85, v92, v92
	v_add_f32_e32 v84, v85, v84
	v_add_f32_e32 v84, v112, v84
	ds_bpermute_b32 v85, v124, v84
	s_waitcnt lgkmcnt(0)
	v_add_f32_e32 v84, v84, v85
	ds_bpermute_b32 v85, v125, v84
	s_and_saveexec_b64 s[0:1], s[36:37]
	s_cbranch_execz .LBB0_831
	s_waitcnt lgkmcnt(0)
	v_add_f32_e32 v86, v84, v85
	v_lshlrev_b64 v[84:85], 7, v[110:111]
	v_lshl_add_u64 v[84:85], s[46:47], 0, v[84:85]
	v_lshl_add_u64 v[84:85], s[14:15], 2, v[84:85]
	s_lshl_b32 s20, s53, 2
	v_lshl_add_u64 v[84:85], v[84:85], 0, s[20:21]
	global_store_dword v[84:85], v86, off
.LBB0_831:
	s_or_b64 exec, exec, s[0:1]
	v_ashrrev_i32_e32 v84, 31, v108
	v_lshrrev_b32_e32 v84, 20, v84
	v_add_u32_e32 v84, v108, v84
	v_ashrrev_i32_e32 v84, 12, v84
	v_mul_i32_i24_e32 v86, 0x1000, v84
	s_waitcnt lgkmcnt(0)
	v_ashrrev_i32_e32 v85, 31, v84
	v_sub_u32_e32 v86, v108, v86
	v_ashrrev_i32_e32 v87, 31, v86
	v_lshlrev_b64 v[84:85], 27, v[84:85]
	v_lshlrev_b64 v[86:87], 13, v[86:87]
	v_lshl_add_u64 v[84:85], s[44:45], 0, v[84:85]
	v_lshl_add_u64 v[84:85], v[84:85], 0, v[86:87]
	s_waitcnt vmcnt(14)
	v_lshlrev_b32_e32 v86, 16, v226
	v_and_b32_e32 v87, 0xffff0000, v226
	v_lshlrev_b32_e32 v88, 16, v227
	v_and_b32_e32 v89, 0xffff0000, v227
	v_lshlrev_b32_e32 v92, 16, v229
	v_and_b32_e32 v93, 0xffff0000, v229
	v_pk_add_f32 v[80:81], v[80:81], v[86:87]
	v_lshlrev_b32_e32 v90, 16, v228
	v_and_b32_e32 v91, 0xffff0000, v228
	v_pk_add_f32 v[82:83], v[82:83], v[88:89]
	v_pk_add_f32 v[86:87], v[78:79], v[92:93]
	v_mul_f32_e32 v79, v81, v81
	v_pk_add_f32 v[88:89], v[76:77], v[90:91]
	v_cvt_pk_bf16_f32 v76, v80, v81
	v_fmac_f32_e32 v79, v80, v80
	v_mul_f32_e32 v80, v83, v83
	v_fmac_f32_e32 v80, v82, v82
	v_add_f32_e32 v79, v79, v80
	v_mul_f32_e32 v80, v89, v89
	v_fmac_f32_e32 v80, v88, v88
	v_add_f32_e32 v79, v80, v79
	v_mul_f32_e32 v80, v87, v87
	v_fmac_f32_e32 v80, v86, v86
	v_cvt_pk_bf16_f32 v77, v82, v83
	v_add_f32_e32 v79, v80, v79
	s_waitcnt vmcnt(14)
	v_lshlrev_b32_e32 v80, 16, v222
	v_and_b32_e32 v81, 0xffff0000, v222
	v_lshlrev_b32_e32 v82, 16, v223
	v_and_b32_e32 v83, 0xffff0000, v223
	v_cvt_pk_bf16_f32 v78, v88, v89
	v_lshlrev_b32_e32 v88, 16, v224
	v_and_b32_e32 v89, 0xffff0000, v224
	v_pk_add_f32 v[74:75], v[74:75], v[82:83]
	v_pk_add_f32 v[72:73], v[72:73], v[80:81]
	v_pk_add_f32 v[82:83], v[68:69], v[88:89]
	v_mul_f32_e32 v68, v73, v73
	v_mul_f32_e32 v69, v75, v75
	v_fmac_f32_e32 v68, v72, v72
	v_fmac_f32_e32 v69, v74, v74
	v_lshlrev_b32_e32 v90, 16, v225
	v_and_b32_e32 v91, 0xffff0000, v225
	v_add_f32_e32 v68, v68, v69
	v_mul_f32_e32 v69, v83, v83
	v_pk_add_f32 v[80:81], v[70:71], v[90:91]
	v_fmac_f32_e32 v69, v82, v82
	v_add_f32_e32 v68, v69, v68
	v_mul_f32_e32 v69, v81, v81
	v_fmac_f32_e32 v69, v80, v80
	v_add_f32_e32 v68, v69, v68
	v_add_f32_e32 v68, v79, v68
	ds_bpermute_b32 v69, v124, v68
	v_lshl_add_u64 v[84:85], v[150:151], 1, v[84:85]
	v_cvt_pk_bf16_f32 v79, v86, v87
	global_store_dwordx4 v[84:85], v[76:79], off nt
	v_cvt_pk_bf16_f32 v70, v72, v73
	s_waitcnt lgkmcnt(0)
	v_add_f32_e32 v68, v68, v69
	ds_bpermute_b32 v69, v125, v68
	v_cvt_pk_bf16_f32 v71, v74, v75
	v_cvt_pk_bf16_f32 v72, v82, v83
	v_cvt_pk_bf16_f32 v73, v80, v81
	global_store_dwordx4 v[84:85], v[70:73], off offset:256 nt
	s_and_saveexec_b64 s[0:1], s[36:37]
	s_cbranch_execz .LBB0_833
	s_waitcnt lgkmcnt(0)
	v_add_f32_e32 v70, v68, v69
	v_lshlrev_b64 v[68:69], 7, v[108:109]
	v_lshl_add_u64 v[68:69], s[46:47], 0, v[68:69]
	v_lshl_add_u64 v[68:69], s[14:15], 2, v[68:69]
	s_lshl_b32 s20, s53, 2
	v_lshl_add_u64 v[68:69], v[68:69], 0, s[20:21]
	global_store_dword v[68:69], v70, off
; __device__ __forceinline__ unsigned cvt_pk_bf16(float lo, float hi) { unsigned r; asm volatile("v_cvt_pk_bf16_f32 %0, %1, %2" : "=v"(r) : "v"(lo), "v"(hi)); return r; }
; #define GAS __attribute__((address_space(1)))
; __device__ __forceinline__ void unpack8(const v4u v, float (&f)[8]) { f[0] = bflo(v.x); f[1] = bfhi(v.x); f[2] = bflo(v.y); f[3] = bfhi(v.y); f[4] = bflo(v.z); f[5] = bfhi(v.z); f[6] = bflo(v.w); f[7] = bfhi(v.w); }
;     __device__ __forceinline__ void operator()(const f32x4 (&acc)[2][2][4][2], const pg8::Unit& u, int wr, int wc, int fr, int fq) const {
;     ...
; #pragma unroll
;         for (int aim = 0; aim < 4; ++aim) { const int ai = aim >> 1, mb = (aim & 1) * 2;
;             v4u hr[4][2];
; #pragma unroll
;             for (int m = mb; m < mb + 2; ++m) { const GAS bf16* hp = h1 + (size_t)(row0 + ai * 128 + m * 16) * DM + col0;
; #pragma unroll
;                 for (int bj = 0; bj < 2; ++bj) hr[m][bj] = *(const GAS v4u*)(hp + bj * 128); }
; #pragma unroll
;             for (int m = mb; m < mb + 2; ++m) { const int row = row0 + ai * 128 + m * 16;
;                 GAS bf16* op = (GAS bf16*)((GAS float*)out + ((size_t)(row / TSEG) * SEQ + (size_t)seg * TSEG + (row % TSEG)) * DM);
;                 float s = 0.f;
; #pragma unroll
;                 for (int bj = 0; bj < 2; ++bj) { const int col = col0 + bj * 128; float hf[8]; unpack8(hr[m][bj], hf);
;                     const f32x4 v0 = acc[ai][bj][m][0] + (f32x4){hf[0], hf[1], hf[2], hf[3]}, v1 = acc[ai][bj][m][1] + (f32x4){hf[4], hf[5], hf[6], hf[7]};
;                     { v4u w; w.x = cvt_pk_bf16(v0[0], v0[1]); w.y = cvt_pk_bf16(v0[2], v0[3]); w.z = cvt_pk_bf16(v1[0], v1[1]); w.w = cvt_pk_bf16(v1[2], v1[3]); __builtin_nontemporal_store(w, (GAS v4u*)(op + col)); }
;                     s += (v0[0] * v0[0] + v0[1] * v0[1]) + (v0[2] * v0[2] + v0[3] * v0[3]) + (v1[0] * v1[0] + v1[1] * v1[1]) + (v1[2] * v1[2] + v1[3] * v1[3]); }
;                 s += __shfl_xor(s, 16); s += __shfl_xor(s, 32);
;                 if (fq == 0) ssq[((size_t)seg * RS + row) * 32 + u.pn * 4 + wc] = s; } }
.LBB0_833:
	s_or_b64 exec, exec, s[0:1]
	v_add_u32_e32 v78, 0x80, v152
	v_ashrrev_i32_e32 v79, 31, v78
	s_waitcnt lgkmcnt(0)
	v_lshlrev_b64 v[68:69], 12, v[78:79]
	v_lshl_add_u64 v[68:69], v[154:155], 0, v[68:69]
	s_nop 0
	s_nop 0
	v_add_u32_e32 v76, 0x90, v152
	v_ashrrev_i32_e32 v77, 31, v76
	v_lshlrev_b64 v[68:69], 12, v[76:77]
	v_lshl_add_u64 v[68:69], v[154:155], 0, v[68:69]
	s_nop 0
	s_nop 0
	s_nop 0
	v_lshrrev_b32_e32 v88, 20, v79
	v_add_u32_e32 v88, v78, v88
	v_ashrrev_i32_e32 v88, 12, v88
	v_mul_i32_i24_e32 v90, 0x1000, v88
	v_ashrrev_i32_e32 v89, 31, v88
	v_sub_u32_e32 v90, v78, v90
	v_ashrrev_i32_e32 v91, 31, v90
	v_lshlrev_b64 v[88:89], 27, v[88:89]
	v_lshlrev_b64 v[90:91], 13, v[90:91]
	v_lshl_add_u64 v[88:89], s[44:45], 0, v[88:89]
	v_lshl_add_u64 v[88:89], v[88:89], 0, v[90:91]
	v_lshl_add_u64 v[88:89], v[150:151], 1, v[88:89]
	s_waitcnt vmcnt(15)
	v_lshlrev_b32_e32 v90, 16, v218
	v_and_b32_e32 v91, 0xffff0000, v218
	v_lshlrev_b32_e32 v80, 16, v219
	v_and_b32_e32 v81, 0xffff0000, v219
	v_lshlrev_b32_e32 v92, 16, v220
	v_and_b32_e32 v93, 0xffff0000, v220
	v_lshlrev_b32_e32 v82, 16, v221
	v_and_b32_e32 v83, 0xffff0000, v221
	v_pk_add_f32 v[66:67], v[66:67], v[80:81]
	v_pk_add_f32 v[64:65], v[64:65], v[90:91]
	v_pk_add_f32 v[80:81], v[62:63], v[82:83]
	v_pk_add_f32 v[82:83], v[60:61], v[92:93]
	v_cvt_pk_bf16_f32 v60, v64, v65
	v_cvt_pk_bf16_f32 v61, v66, v67
	s_nop 0
	v_cvt_pk_bf16_f32 v62, v82, v83
	v_cvt_pk_bf16_f32 v63, v80, v81
	global_store_dwordx4 v[88:89], v[60:63], off nt
	s_nop 1
	v_mul_f32_e32 v60, v65, v65
	v_mul_f32_e32 v61, v67, v67
	v_fmac_f32_e32 v60, v64, v64
	v_fmac_f32_e32 v61, v66, v66
	v_add_f32_e32 v60, v60, v61
	v_mul_f32_e32 v61, v83, v83
	v_fmac_f32_e32 v61, v82, v82
	v_add_f32_e32 v60, v61, v60
	v_mul_f32_e32 v61, v81, v81
	v_fmac_f32_e32 v61, v80, v80
	v_add_f32_e32 v80, v61, v60
	s_waitcnt vmcnt(15)
	v_lshlrev_b32_e32 v60, 16, v214
	v_and_b32_e32 v61, 0xffff0000, v214
	v_lshlrev_b32_e32 v62, 16, v215
	v_and_b32_e32 v63, 0xffff0000, v215
	v_lshlrev_b32_e32 v64, 16, v216
	v_and_b32_e32 v65, 0xffff0000, v216
	v_lshlrev_b32_e32 v66, 16, v217
	v_and_b32_e32 v67, 0xffff0000, v217
	v_pk_add_f32 v[58:59], v[58:59], v[62:63]
	v_pk_add_f32 v[56:57], v[56:57], v[60:61]
	v_pk_add_f32 v[62:63], v[52:53], v[64:65]
	v_cvt_pk_bf16_f32 v52, v56, v57
	v_cvt_pk_bf16_f32 v53, v58, v59
	v_pk_add_f32 v[60:61], v[54:55], v[66:67]
	v_cvt_pk_bf16_f32 v54, v62, v63
	s_nop 0
	v_cvt_pk_bf16_f32 v55, v60, v61
	global_store_dwordx4 v[88:89], v[52:55], off offset:256 nt
	s_nop 1
	v_mul_f32_e32 v52, v57, v57
	v_mul_f32_e32 v53, v59, v59
	v_fmac_f32_e32 v52, v56, v56
	v_fmac_f32_e32 v53, v58, v58
	v_add_f32_e32 v52, v52, v53
	v_mul_f32_e32 v53, v63, v63
	v_fmac_f32_e32 v53, v62, v62
	v_add_f32_e32 v52, v53, v52
	v_mul_f32_e32 v53, v61, v61
	v_fmac_f32_e32 v53, v60, v60
	v_add_f32_e32 v52, v53, v52
	v_add_f32_e32 v52, v80, v52
	ds_bpermute_b32 v53, v124, v52
	s_waitcnt lgkmcnt(0)
	v_add_f32_e32 v52, v52, v53
	ds_bpermute_b32 v53, v125, v52
	s_and_saveexec_b64 s[0:1], s[36:37]
	s_cbranch_execz .LBB0_835
	s_waitcnt lgkmcnt(0)
	v_add_f32_e32 v54, v52, v53
	v_lshlrev_b64 v[52:53], 7, v[78:79]
	v_lshl_add_u64 v[52:53], s[46:47], 0, v[52:53]
	v_lshl_add_u64 v[52:53], s[14:15], 2, v[52:53]
	s_lshl_b32 s20, s53, 2
	v_lshl_add_u64 v[52:53], v[52:53], 0, s[20:21]
	global_store_dword v[52:53], v54, off
.LBB0_835:
	s_or_b64 exec, exec, s[0:1]
	v_ashrrev_i32_e32 v52, 31, v76
	v_lshrrev_b32_e32 v52, 20, v52
	v_add_u32_e32 v52, v76, v52
	v_ashrrev_i32_e32 v52, 12, v52
	v_mul_i32_i24_e32 v54, 0x1000, v52
	s_waitcnt lgkmcnt(0)
	v_ashrrev_i32_e32 v53, 31, v52
	v_sub_u32_e32 v54, v76, v54
	v_ashrrev_i32_e32 v55, 31, v54
	v_lshlrev_b64 v[52:53], 27, v[52:53]
	v_lshlrev_b64 v[54:55], 13, v[54:55]
	v_lshl_add_u64 v[52:53], s[44:45], 0, v[52:53]
	v_lshl_add_u64 v[52:53], v[52:53], 0, v[54:55]
	s_waitcnt vmcnt(14)
	v_lshlrev_b32_e32 v54, 16, v210
	v_and_b32_e32 v55, 0xffff0000, v210
	v_lshlrev_b32_e32 v56, 16, v211
	v_and_b32_e32 v57, 0xffff0000, v211
	v_lshlrev_b32_e32 v60, 16, v213
	v_and_b32_e32 v61, 0xffff0000, v213
	v_pk_add_f32 v[48:49], v[48:49], v[54:55]
	v_lshlrev_b32_e32 v58, 16, v212
	v_and_b32_e32 v59, 0xffff0000, v212
	v_pk_add_f32 v[50:51], v[50:51], v[56:57]
	v_pk_add_f32 v[54:55], v[46:47], v[60:61]
	v_mul_f32_e32 v47, v49, v49
	v_pk_add_f32 v[56:57], v[44:45], v[58:59]
	v_cvt_pk_bf16_f32 v44, v48, v49
	v_fmac_f32_e32 v47, v48, v48
	v_mul_f32_e32 v48, v51, v51
	v_fmac_f32_e32 v48, v50, v50
	v_add_f32_e32 v47, v47, v48
	v_mul_f32_e32 v48, v57, v57
	v_fmac_f32_e32 v48, v56, v56
	v_add_f32_e32 v47, v48, v47
	v_mul_f32_e32 v48, v55, v55
	v_fmac_f32_e32 v48, v54, v54
	v_cvt_pk_bf16_f32 v45, v50, v51
	v_add_f32_e32 v47, v48, v47
	s_waitcnt vmcnt(14)
	v_lshlrev_b32_e32 v48, 16, v206
	v_and_b32_e32 v49, 0xffff0000, v206
	v_lshlrev_b32_e32 v50, 16, v207
	v_and_b32_e32 v51, 0xffff0000, v207
	v_cvt_pk_bf16_f32 v46, v56, v57
	v_lshlrev_b32_e32 v56, 16, v208
	v_and_b32_e32 v57, 0xffff0000, v208
	v_pk_add_f32 v[42:43], v[42:43], v[50:51]
	v_pk_add_f32 v[40:41], v[40:41], v[48:49]
	v_pk_add_f32 v[50:51], v[36:37], v[56:57]
	v_mul_f32_e32 v36, v41, v41
	v_mul_f32_e32 v37, v43, v43
	v_fmac_f32_e32 v36, v40, v40
	v_fmac_f32_e32 v37, v42, v42
	v_lshlrev_b32_e32 v58, 16, v209
	v_and_b32_e32 v59, 0xffff0000, v209
	v_add_f32_e32 v36, v36, v37
	v_mul_f32_e32 v37, v51, v51
	v_pk_add_f32 v[48:49], v[38:39], v[58:59]
	v_fmac_f32_e32 v37, v50, v50
	v_add_f32_e32 v36, v37, v36
	v_mul_f32_e32 v37, v49, v49
	v_fmac_f32_e32 v37, v48, v48
	v_add_f32_e32 v36, v37, v36
	v_add_f32_e32 v36, v47, v36
	ds_bpermute_b32 v37, v124, v36
	v_lshl_add_u64 v[52:53], v[150:151], 1, v[52:53]
	v_cvt_pk_bf16_f32 v47, v54, v55
	global_store_dwordx4 v[52:53], v[44:47], off nt
	v_cvt_pk_bf16_f32 v38, v40, v41
	s_waitcnt lgkmcnt(0)
	v_add_f32_e32 v36, v36, v37
	ds_bpermute_b32 v37, v125, v36
	v_cvt_pk_bf16_f32 v39, v42, v43
	v_cvt_pk_bf16_f32 v40, v50, v51
	v_cvt_pk_bf16_f32 v41, v48, v49
	global_store_dwordx4 v[52:53], v[38:41], off offset:256 nt
	s_and_saveexec_b64 s[0:1], s[36:37]
	s_cbranch_execz .LBB0_837
	s_waitcnt lgkmcnt(0)
	v_add_f32_e32 v38, v36, v37
	v_lshlrev_b64 v[36:37], 7, v[76:77]
	v_lshl_add_u64 v[36:37], s[46:47], 0, v[36:37]
	v_lshl_add_u64 v[36:37], s[14:15], 2, v[36:37]
	s_lshl_b32 s20, s53, 2
	v_lshl_add_u64 v[36:37], v[36:37], 0, s[20:21]
	global_store_dword v[36:37], v38, off
; __device__ __forceinline__ unsigned cvt_pk_bf16(float lo, float hi) { unsigned r; asm volatile("v_cvt_pk_bf16_f32 %0, %1, %2" : "=v"(r) : "v"(lo), "v"(hi)); return r; }
; #define GAS __attribute__((address_space(1)))
; __device__ __forceinline__ void unpack8(const v4u v, float (&f)[8]) { f[0] = bflo(v.x); f[1] = bfhi(v.x); f[2] = bflo(v.y); f[3] = bfhi(v.y); f[4] = bflo(v.z); f[5] = bfhi(v.z); f[6] = bflo(v.w); f[7] = bfhi(v.w); }
;     __device__ __forceinline__ void operator()(const f32x4 (&acc)[2][2][4][2], const pg8::Unit& u, int wr, int wc, int fr, int fq) const {
;     ...
; #pragma unroll
;         for (int aim = 0; aim < 4; ++aim) { const int ai = aim >> 1, mb = (aim & 1) * 2;
;             v4u hr[4][2];
; #pragma unroll
;             for (int m = mb; m < mb + 2; ++m) { const GAS bf16* hp = h1 + (size_t)(row0 + ai * 128 + m * 16) * DM + col0;
; #pragma unroll
;                 for (int bj = 0; bj < 2; ++bj) hr[m][bj] = *(const GAS v4u*)(hp + bj * 128); }
; #pragma unroll
;             for (int m = mb; m < mb + 2; ++m) { const int row = row0 + ai * 128 + m * 16;
;                 GAS bf16* op = (GAS bf16*)((GAS float*)out + ((size_t)(row / TSEG) * SEQ + (size_t)seg * TSEG + (row % TSEG)) * DM);
;                 float s = 0.f;
; #pragma unroll
;                 for (int bj = 0; bj < 2; ++bj) { const int col = col0 + bj * 128; float hf[8]; unpack8(hr[m][bj], hf);
;                     const f32x4 v0 = acc[ai][bj][m][0] + (f32x4){hf[0], hf[1], hf[2], hf[3]}, v1 = acc[ai][bj][m][1] + (f32x4){hf[4], hf[5], hf[6], hf[7]};
;                     { v4u w; w.x = cvt_pk_bf16(v0[0], v0[1]); w.y = cvt_pk_bf16(v0[2], v0[3]); w.z = cvt_pk_bf16(v1[0], v1[1]); w.w = cvt_pk_bf16(v1[2], v1[3]); __builtin_nontemporal_store(w, (GAS v4u*)(op + col)); }
;                     s += (v0[0] * v0[0] + v0[1] * v0[1]) + (v0[2] * v0[2] + v0[3] * v0[3]) + (v1[0] * v1[0] + v1[1] * v1[1]) + (v1[2] * v1[2] + v1[3] * v1[3]); }
;                 s += __shfl_xor(s, 16); s += __shfl_xor(s, 32);
;                 if (fq == 0) ssq[((size_t)seg * RS + row) * 32 + u.pn * 4 + wc] = s; } }
.LBB0_837:
	s_or_b64 exec, exec, s[0:1]
	v_add_u32_e32 v46, 0xa0, v152
	v_ashrrev_i32_e32 v47, 31, v46
	s_waitcnt lgkmcnt(0)
	v_lshlrev_b64 v[36:37], 12, v[46:47]
	v_lshl_add_u64 v[36:37], v[154:155], 0, v[36:37]
	s_nop 0
	s_nop 0
	v_add_u32_e32 v44, 0xb0, v152
	v_ashrrev_i32_e32 v45, 31, v44
	v_lshlrev_b64 v[36:37], 12, v[44:45]
	v_lshl_add_u64 v[36:37], v[154:155], 0, v[36:37]
	s_nop 0
	s_nop 0
	s_nop 0
	v_lshrrev_b32_e32 v56, 20, v47
	v_add_u32_e32 v56, v46, v56
	v_ashrrev_i32_e32 v56, 12, v56
	v_mul_i32_i24_e32 v58, 0x1000, v56
	v_ashrrev_i32_e32 v57, 31, v56
	v_sub_u32_e32 v58, v46, v58
	v_ashrrev_i32_e32 v59, 31, v58
	v_lshlrev_b64 v[56:57], 27, v[56:57]
	v_lshlrev_b64 v[58:59], 13, v[58:59]
	v_lshl_add_u64 v[56:57], s[44:45], 0, v[56:57]
	v_lshl_add_u64 v[56:57], v[56:57], 0, v[58:59]
	v_lshl_add_u64 v[56:57], v[150:151], 1, v[56:57]
	s_waitcnt vmcnt(15)
	v_lshlrev_b32_e32 v58, 16, v202
	v_and_b32_e32 v59, 0xffff0000, v202
	v_lshlrev_b32_e32 v48, 16, v203
	v_and_b32_e32 v49, 0xffff0000, v203
	v_lshlrev_b32_e32 v60, 16, v204
	v_and_b32_e32 v61, 0xffff0000, v204
	v_lshlrev_b32_e32 v50, 16, v205
	v_and_b32_e32 v51, 0xffff0000, v205
	v_pk_add_f32 v[34:35], v[34:35], v[48:49]
	v_pk_add_f32 v[32:33], v[32:33], v[58:59]
	v_pk_add_f32 v[48:49], v[30:31], v[50:51]
	v_pk_add_f32 v[50:51], v[28:29], v[60:61]
	v_cvt_pk_bf16_f32 v28, v32, v33
	v_cvt_pk_bf16_f32 v29, v34, v35
	s_nop 0
	v_cvt_pk_bf16_f32 v30, v50, v51
	v_cvt_pk_bf16_f32 v31, v48, v49
	global_store_dwordx4 v[56:57], v[28:31], off nt
	s_nop 1
	v_mul_f32_e32 v28, v33, v33
	v_mul_f32_e32 v29, v35, v35
	v_fmac_f32_e32 v28, v32, v32
	v_fmac_f32_e32 v29, v34, v34
	v_add_f32_e32 v28, v28, v29
	v_mul_f32_e32 v29, v51, v51
	v_fmac_f32_e32 v29, v50, v50
	v_add_f32_e32 v28, v29, v28
	v_mul_f32_e32 v29, v49, v49
	v_fmac_f32_e32 v29, v48, v48
	v_add_f32_e32 v48, v29, v28
	s_waitcnt vmcnt(15)
	v_lshlrev_b32_e32 v28, 16, v198
	v_and_b32_e32 v29, 0xffff0000, v198
	v_lshlrev_b32_e32 v30, 16, v199
	v_and_b32_e32 v31, 0xffff0000, v199
	v_lshlrev_b32_e32 v32, 16, v200
	v_and_b32_e32 v33, 0xffff0000, v200
	v_lshlrev_b32_e32 v34, 16, v201
	v_and_b32_e32 v35, 0xffff0000, v201
	v_pk_add_f32 v[26:27], v[26:27], v[30:31]
	v_pk_add_f32 v[24:25], v[24:25], v[28:29]
	v_pk_add_f32 v[30:31], v[20:21], v[32:33]
	v_cvt_pk_bf16_f32 v20, v24, v25
	v_cvt_pk_bf16_f32 v21, v26, v27
	v_pk_add_f32 v[28:29], v[22:23], v[34:35]
	v_cvt_pk_bf16_f32 v22, v30, v31
	s_nop 0
	v_cvt_pk_bf16_f32 v23, v28, v29
	global_store_dwordx4 v[56:57], v[20:23], off offset:256 nt
	s_nop 1
	v_mul_f32_e32 v20, v25, v25
	v_mul_f32_e32 v21, v27, v27
	v_fmac_f32_e32 v20, v24, v24
	v_fmac_f32_e32 v21, v26, v26
	v_add_f32_e32 v20, v20, v21
	v_mul_f32_e32 v21, v31, v31
	v_fmac_f32_e32 v21, v30, v30
	v_add_f32_e32 v20, v21, v20
	v_mul_f32_e32 v21, v29, v29
	v_fmac_f32_e32 v21, v28, v28
	v_add_f32_e32 v20, v21, v20
	v_add_f32_e32 v20, v48, v20
	ds_bpermute_b32 v21, v124, v20
	s_waitcnt lgkmcnt(0)
	v_add_f32_e32 v20, v20, v21
	ds_bpermute_b32 v21, v125, v20
	s_and_saveexec_b64 s[0:1], s[36:37]
	s_cbranch_execz .LBB0_839
	s_waitcnt lgkmcnt(0)
	v_add_f32_e32 v22, v20, v21
	v_lshlrev_b64 v[20:21], 7, v[46:47]
	v_lshl_add_u64 v[20:21], s[46:47], 0, v[20:21]
	v_lshl_add_u64 v[20:21], s[14:15], 2, v[20:21]
	s_lshl_b32 s20, s53, 2
	v_lshl_add_u64 v[20:21], v[20:21], 0, s[20:21]
	global_store_dword v[20:21], v22, off
.LBB0_839:
	s_or_b64 exec, exec, s[0:1]
	v_ashrrev_i32_e32 v20, 31, v44
	v_lshrrev_b32_e32 v20, 20, v20
	v_add_u32_e32 v20, v44, v20
	v_ashrrev_i32_e32 v20, 12, v20
	v_mul_i32_i24_e32 v22, 0x1000, v20
	s_waitcnt lgkmcnt(0)
	v_ashrrev_i32_e32 v21, 31, v20
	v_sub_u32_e32 v22, v44, v22
	v_ashrrev_i32_e32 v23, 31, v22
	v_lshlrev_b64 v[20:21], 27, v[20:21]
	v_lshlrev_b64 v[22:23], 13, v[22:23]
	v_lshl_add_u64 v[20:21], s[44:45], 0, v[20:21]
	v_lshl_add_u64 v[20:21], v[20:21], 0, v[22:23]
	s_waitcnt vmcnt(14)
	v_lshlrev_b32_e32 v22, 16, v194
	v_and_b32_e32 v23, 0xffff0000, v194
	v_lshlrev_b32_e32 v24, 16, v195
	v_and_b32_e32 v25, 0xffff0000, v195
	v_lshlrev_b32_e32 v28, 16, v197
	v_and_b32_e32 v29, 0xffff0000, v197
	v_pk_add_f32 v[16:17], v[16:17], v[22:23]
	v_lshlrev_b32_e32 v26, 16, v196
	v_and_b32_e32 v27, 0xffff0000, v196
	v_pk_add_f32 v[18:19], v[18:19], v[24:25]
	v_pk_add_f32 v[22:23], v[14:15], v[28:29]
	v_mul_f32_e32 v15, v17, v17
	v_pk_add_f32 v[24:25], v[12:13], v[26:27]
	v_cvt_pk_bf16_f32 v12, v16, v17
	v_fmac_f32_e32 v15, v16, v16
	v_mul_f32_e32 v16, v19, v19
	v_fmac_f32_e32 v16, v18, v18
	v_add_f32_e32 v15, v15, v16
	v_mul_f32_e32 v16, v25, v25
	v_fmac_f32_e32 v16, v24, v24
	v_add_f32_e32 v15, v16, v15
	v_mul_f32_e32 v16, v23, v23
	v_fmac_f32_e32 v16, v22, v22
	v_cvt_pk_bf16_f32 v13, v18, v19
	v_add_f32_e32 v15, v16, v15
	s_waitcnt vmcnt(14)
	v_lshlrev_b32_e32 v16, 16, v190
	v_and_b32_e32 v17, 0xffff0000, v190
	v_lshlrev_b32_e32 v18, 16, v191
	v_and_b32_e32 v19, 0xffff0000, v191
	v_cvt_pk_bf16_f32 v14, v24, v25
	v_lshlrev_b32_e32 v24, 16, v192
	v_and_b32_e32 v25, 0xffff0000, v192
	v_pk_add_f32 v[10:11], v[10:11], v[18:19]
	v_pk_add_f32 v[8:9], v[8:9], v[16:17]
	v_pk_add_f32 v[18:19], v[4:5], v[24:25]
	v_mul_f32_e32 v4, v9, v9
	v_mul_f32_e32 v5, v11, v11
	v_fmac_f32_e32 v4, v8, v8
	v_fmac_f32_e32 v5, v10, v10
	v_lshlrev_b32_e32 v26, 16, v193
	v_and_b32_e32 v27, 0xffff0000, v193
	v_add_f32_e32 v4, v4, v5
	v_mul_f32_e32 v5, v19, v19
	v_pk_add_f32 v[16:17], v[6:7], v[26:27]
	v_fmac_f32_e32 v5, v18, v18
	v_add_f32_e32 v4, v5, v4
	v_mul_f32_e32 v5, v17, v17
	v_fmac_f32_e32 v5, v16, v16
	v_add_f32_e32 v4, v5, v4
	v_add_f32_e32 v4, v15, v4
	ds_bpermute_b32 v5, v124, v4
	v_lshl_add_u64 v[20:21], v[150:151], 1, v[20:21]
	v_cvt_pk_bf16_f32 v15, v22, v23
	global_store_dwordx4 v[20:21], v[12:15], off nt
	v_cvt_pk_bf16_f32 v6, v8, v9
	s_waitcnt lgkmcnt(0)
	v_add_f32_e32 v4, v4, v5
	ds_bpermute_b32 v5, v125, v4
	v_cvt_pk_bf16_f32 v7, v10, v11
	v_cvt_pk_bf16_f32 v8, v18, v19
	v_cvt_pk_bf16_f32 v9, v16, v17
	global_store_dwordx4 v[20:21], v[6:9], off offset:256 nt
	s_and_saveexec_b64 s[0:1], s[36:37]
	s_cbranch_execz .LBB0_841
	s_waitcnt lgkmcnt(0)
	v_add_f32_e32 v6, v4, v5
	v_lshlrev_b64 v[4:5], 7, v[44:45]
	v_lshl_add_u64 v[4:5], s[46:47], 0, v[4:5]
	v_lshl_add_u64 v[4:5], s[14:15], 2, v[4:5]
	s_lshl_b32 s20, s53, 2
	v_lshl_add_u64 v[4:5], v[4:5], 0, s[20:21]
	global_store_dword v[4:5], v6, off
